# attention: staging loads at QK^T slots 6/14/22/30
# baseline (speedup 1.0000x reference)
; __device__ __forceinline__ void finishSM(f32x16& p0, f32x16& p1, float& l_reg, bf16x8& pa0, bf16x8& pa1, bf16x8& pa2, bf16x8& pa3) {
;   for (int r = 0; r < 16; ++r) p1[r] = __builtin_amdgcn_exp2f(p1[r]);
;   float ps = 0; for (int r = 0; r < 16; ++r) ps += p0[r]; for (int r = 0; r < 16; ++r) ps += p1[r];
;   { auto rr = __builtin_amdgcn_permlane32_swap(__float_as_uint(ps), __float_as_uint(ps), false, false);
;     ps = __uint_as_float(rr[0]) + __uint_as_float(rr[1]); }
;   l_reg += ps;
;     ...
;   PK4(p0, 0, pa0); PK4(p0, 8, pa1); PK4(p1, 0, pa2); PK4(p1, 8, pa3);
;     ...
; }
; __device__ __forceinline__ void qkt(f32x16& p0, f32x16& p1, const bf16* Ks, const bf16x8* qr, int r32, int hi, const f32x16& negm) {
; #pragma unroll
;   for (int d0 = 0; d0 < 8; ++d0) { int cb = (d0 * 16 + hi * 8) * 2;
;     bf16x8 b0 = *reinterpret_cast<const bf16x8*>((const char*)Ks + KSWZ(r32, cb));
;     bf16x8 b1 = *reinterpret_cast<const bf16x8*>((const char*)Ks + KSWZ(32 + r32, cb));
;     if (d0 == 0) { p0 = __builtin_amdgcn_mfma_f32_32x32x16_bf16(b0, qr[0], negm, 0, 0, 0); p1 = __builtin_amdgcn_mfma_f32_32x32x16_bf16(b1, qr[0], negm, 0, 0, 0); }
;     else { p0 = __builtin_amdgcn_mfma_f32_32x32x16_bf16(b0, qr[d0], p0, 0, 0, 0); p1 = __builtin_amdgcn_mfma_f32_32x32x16_bf16(b1, qr[d0], p1, 0, 0, 0); } }
; }
.Lattn_loop:
	s_barrier
	s_waitcnt lgkmcnt(3)
	v_mfma_f32_16x16x32_bf16 v[114:117], v[178:181], v[146:149], v[2:5]
	v_add_f32_e32 v250, v82, v250
	s_add_u32 s98, s98, 0x8000
	s_addc_u32 s99, s99, 0
	s_add_u32 s100, s100, 0x8000
	s_addc_u32 s101, s101, 0
	v_mfma_f32_16x16x32_bf16 v[118:121], v[178:181], v[162:165], v[2:5]
	ds_read_b128 v[178:181], v235 offset:16384
	v_add_f32_e32 v250, v83, v250
	v_add_f32_e32 v250, v84, v250
	s_waitcnt lgkmcnt(3)
	v_mfma_f32_16x16x32_bf16 v[122:125], v[182:185], v[146:149], v[2:5]
	v_add_f32_e32 v250, v85, v250
	v_mfma_f32_16x16x32_bf16 v[126:129], v[182:185], v[162:165], v[2:5]
	ds_read_b128 v[182:185], v235 offset:20480
	v_add_f32_e32 v250, v90, v250
	v_add_f32_e32 v250, v91, v250
	s_waitcnt lgkmcnt(3)
	v_mfma_f32_16x16x32_bf16 v[130:133], v[186:189], v[146:149], v[2:5]
	v_add_f32_e32 v250, v92, v250
	v_mfma_f32_16x16x32_bf16 v[134:137], v[186:189], v[162:165], v[2:5]
	ds_read_b128 v[186:189], v235 offset:24576
	v_add_f32_e32 v250, v93, v250
	v_cvt_pk_bf16_f32 v82, v82, v83
	s_waitcnt lgkmcnt(3)
	v_mfma_f32_16x16x32_bf16 v[138:141], v[190:193], v[146:149], v[2:5]
	v_cvt_pk_bf16_f32 v83, v84, v85
	s_add_u32 m0, s79, 0
	s_nop 0
	global_load_lds_dwordx4 v246, s[98:99]
	v_mfma_f32_16x16x32_bf16 v[142:145], v[190:193], v[162:165], v[2:5]
	ds_read_b128 v[190:193], v235 offset:28672
	v_cvt_pk_bf16_f32 v84, v90, v91
	v_cvt_pk_bf16_f32 v85, v92, v93
	s_waitcnt lgkmcnt(3)
	v_mfma_f32_16x16x32_bf16 v[114:117], v[178:181], v[150:153], v[114:117]
	v_add_f32_e32 v251, v86, v251
	v_mfma_f32_16x16x32_bf16 v[118:121], v[178:181], v[166:169], v[118:121]
	ds_read_b128 v[178:181], v236 offset:16384
	v_add_f32_e32 v251, v87, v251
	v_add_f32_e32 v251, v88, v251
	s_waitcnt lgkmcnt(3)
	v_mfma_f32_16x16x32_bf16 v[122:125], v[182:185], v[150:153], v[122:125]
	v_add_f32_e32 v251, v89, v251
	v_mfma_f32_16x16x32_bf16 v[126:129], v[182:185], v[166:169], v[126:129]
	ds_read_b128 v[182:185], v236 offset:20480
	v_add_f32_e32 v251, v94, v251
	v_add_f32_e32 v251, v95, v251
	s_waitcnt lgkmcnt(3)
	v_mfma_f32_16x16x32_bf16 v[130:133], v[186:189], v[150:153], v[130:133]
	v_add_f32_e32 v251, v96, v251
	v_mfma_f32_16x16x32_bf16 v[134:137], v[186:189], v[166:169], v[134:137]
	ds_read_b128 v[186:189], v236 offset:24576
	v_add_f32_e32 v251, v97, v251
	v_cvt_pk_bf16_f32 v86, v86, v87
	s_waitcnt lgkmcnt(3)
	v_mfma_f32_16x16x32_bf16 v[138:141], v[190:193], v[150:153], v[138:141]
	v_cvt_pk_bf16_f32 v87, v88, v89
	s_add_u32 m0, s79, 1024
	s_nop 0
	global_load_lds_dwordx4 v247, s[98:99]
	v_mfma_f32_16x16x32_bf16 v[142:145], v[190:193], v[166:169], v[142:145]
	ds_read_b128 v[190:193], v236 offset:28672
	v_cvt_pk_bf16_f32 v88, v94, v95
	v_cvt_pk_bf16_f32 v89, v96, v97
	s_waitcnt lgkmcnt(3)
	v_mfma_f32_16x16x32_bf16 v[114:117], v[178:181], v[154:157], v[114:117]
	v_add_f32_e32 v250, v98, v250
	v_mfma_f32_16x16x32_bf16 v[118:121], v[178:181], v[170:173], v[118:121]
	ds_read_b128 v[178:181], v237 offset:16384
	v_add_f32_e32 v250, v99, v250
	v_add_f32_e32 v250, v100, v250
	s_waitcnt lgkmcnt(3)
	v_mfma_f32_16x16x32_bf16 v[122:125], v[182:185], v[154:157], v[122:125]
	v_add_f32_e32 v250, v101, v250
	v_mfma_f32_16x16x32_bf16 v[126:129], v[182:185], v[170:173], v[126:129]
	ds_read_b128 v[182:185], v237 offset:20480
	v_add_f32_e32 v250, v106, v250
	v_add_f32_e32 v250, v107, v250
	s_waitcnt lgkmcnt(3)
	v_mfma_f32_16x16x32_bf16 v[130:133], v[186:189], v[154:157], v[130:133]
	v_add_f32_e32 v250, v108, v250
	ds_read_b64_tr_b16 v[202:203], v238 offset:0
	ds_read_b64_tr_b16 v[204:205], v238 offset:4096
	v_mfma_f32_16x16x32_bf16 v[134:137], v[186:189], v[170:173], v[134:137]
	ds_read_b128 v[186:189], v237 offset:24576
	v_add_f32_e32 v250, v109, v250
	v_cvt_pk_bf16_f32 v98, v98, v99
	s_waitcnt lgkmcnt(5)
	v_mfma_f32_16x16x32_bf16 v[138:141], v[190:193], v[154:157], v[138:141]
	v_cvt_pk_bf16_f32 v99, v100, v101
	s_add_u32 m0, s80, 49152
	s_nop 0
	global_load_lds_dwordx4 v248, s[100:101]
	ds_read_b64_tr_b16 v[206:207], v239 offset:0
	ds_read_b64_tr_b16 v[208:209], v239 offset:4096
	v_mfma_f32_16x16x32_bf16 v[142:145], v[190:193], v[170:173], v[142:145]
	ds_read_b128 v[190:193], v237 offset:28672
	v_cvt_pk_bf16_f32 v100, v106, v107
	v_cvt_pk_bf16_f32 v101, v108, v109
	s_waitcnt lgkmcnt(7)
	v_mfma_f32_16x16x32_bf16 v[114:117], v[178:181], v[158:161], v[114:117]
	v_add_f32_e32 v251, v102, v251
	ds_read_b64_tr_b16 v[210:211], v240 offset:0
	ds_read_b64_tr_b16 v[212:213], v240 offset:4096
	v_mfma_f32_16x16x32_bf16 v[118:121], v[178:181], v[174:177], v[118:121]
	v_add_f32_e32 v251, v103, v251
	v_add_f32_e32 v251, v104, v251
	s_waitcnt lgkmcnt(8)
	v_mfma_f32_16x16x32_bf16 v[122:125], v[182:185], v[158:161], v[122:125]
	v_add_f32_e32 v251, v105, v251
	ds_read_b64_tr_b16 v[214:215], v241 offset:0
	ds_read_b64_tr_b16 v[216:217], v241 offset:4096
	v_mfma_f32_16x16x32_bf16 v[126:129], v[182:185], v[174:177], v[126:129]
	v_add_f32_e32 v251, v110, v251
	v_add_f32_e32 v251, v111, v251
	s_waitcnt lgkmcnt(7)
	v_mfma_f32_16x16x32_bf16 v[130:133], v[186:189], v[158:161], v[130:133]
	v_add_f32_e32 v251, v112, v251
	ds_read_b64_tr_b16 v[218:219], v242 offset:0
	ds_read_b64_tr_b16 v[220:221], v242 offset:4096
	v_mfma_f32_16x16x32_bf16 v[134:137], v[186:189], v[174:177], v[134:137]
	v_add_f32_e32 v251, v113, v251
	v_cvt_pk_bf16_f32 v102, v102, v103
	s_waitcnt lgkmcnt(6)
; #define SBAR() __builtin_amdgcn_sched_barrier(0)
; __device__ __forceinline__ void qkt(f32x16& p0, f32x16& p1, const bf16* Ks, const bf16x8* qr, int r32, int hi, const f32x16& negm) {
; #pragma unroll
;   for (int d0 = 0; d0 < 8; ++d0) { int cb = (d0 * 16 + hi * 8) * 2;
;     bf16x8 b0 = *reinterpret_cast<const bf16x8*>((const char*)Ks + KSWZ(r32, cb));
;     bf16x8 b1 = *reinterpret_cast<const bf16x8*>((const char*)Ks + KSWZ(32 + r32, cb));
;     if (d0 == 0) { p0 = __builtin_amdgcn_mfma_f32_32x32x16_bf16(b0, qr[0], negm, 0, 0, 0); p1 = __builtin_amdgcn_mfma_f32_32x32x16_bf16(b1, qr[0], negm, 0, 0, 0); }
;     else { p0 = __builtin_amdgcn_mfma_f32_32x32x16_bf16(b0, qr[d0], p0, 0, 0, 0); p1 = __builtin_amdgcn_mfma_f32_32x32x16_bf16(b1, qr[d0], p1, 0, 0, 0); } }
; }
; template <int D0> __device__ __forceinline__ void pv_one(f32x16& od, int vb, bf16x8 pa0, bf16x8 pa1, bf16x8 pa2, bf16x8 pa3) {
;   const s16x4 l0 = tr_read<v_rd_off(D0, 0, 0)>(vb), h0 = tr_read<v_rd_off(D0, 0, 1)>(vb), l1 = tr_read<v_rd_off(D0, 1, 0)>(vb), h1 = tr_read<v_rd_off(D0, 1, 1)>(vb);
;   const s16x4 l2 = tr_read<v_rd_off(D0, 2, 0)>(vb), h2 = tr_read<v_rd_off(D0, 2, 1)>(vb), l3 = tr_read<v_rd_off(D0, 3, 0)>(vb), h3 = tr_read<v_rd_off(D0, 3, 1)>(vb);
;   asm volatile("s_waitcnt lgkmcnt(0)" ::: "memory"); SBAR();
;     ...
;   od = __builtin_amdgcn_mfma_f32_32x32x16_bf16(pa0, PK(l0, h0), od, 0, 0, 0);
;   od = __builtin_amdgcn_mfma_f32_32x32x16_bf16(pa1, PK(l1, h1), od, 0, 0, 0);
;   od = __builtin_amdgcn_mfma_f32_32x32x16_bf16(pa2, PK(l2, h2), od, 0, 0, 0);
;   od = __builtin_amdgcn_mfma_f32_32x32x16_bf16(pa3, PK(l3, h3), od, 0, 0, 0);
;     ...
; }
; __device__ __forceinline__ void pv_d0(f32x16* o, int vb, bf16x8 pa0, bf16x8 pa1, bf16x8 pa2, bf16x8 pa3) {
;   pv_one<0>(o[0], vb, pa0, pa1, pa2, pa3); pv_one<1>(o[1], vb, pa0, pa1, pa2, pa3); pv_one<2>(o[2], vb, pa0, pa1, pa2, pa3); pv_one<3>(o[3], vb, pa0, pa1, pa2, pa3);
	v_mfma_f32_16x16x32_bf16 v[138:141], v[190:193], v[158:161], v[138:141]
	v_cvt_pk_bf16_f32 v103, v104, v105
	s_add_u32 m0, s80, 50176
	s_nop 0
	global_load_lds_dwordx4 v249, s[100:101]
	ds_read_b64_tr_b16 v[222:223], v243 offset:0
	ds_read_b64_tr_b16 v[224:225], v243 offset:4096
	v_mfma_f32_16x16x32_bf16 v[142:145], v[190:193], v[174:177], v[142:145]
	v_cvt_pk_bf16_f32 v104, v110, v111
	v_cvt_pk_bf16_f32 v105, v112, v113
	v_mfma_f32_16x16x32_bf16 v[18:21], v[202:205], v[82:85], v[18:21]
	v_exp_f32_e32 v114, v114
	v_mfma_f32_16x16x32_bf16 v[22:25], v[202:205], v[86:89], v[22:25]
	ds_read_b64_tr_b16 v[202:203], v244 offset:0
	ds_read_b64_tr_b16 v[204:205], v244 offset:4096
	v_exp_f32_e32 v115, v115
	v_mfma_f32_16x16x32_bf16 v[26:29], v[206:209], v[82:85], v[26:29]
	v_exp_f32_e32 v116, v116
	v_mfma_f32_16x16x32_bf16 v[30:33], v[206:209], v[86:89], v[30:33]
	ds_read_b64_tr_b16 v[206:207], v245 offset:0
	ds_read_b64_tr_b16 v[208:209], v245 offset:4096
	v_exp_f32_e32 v117, v117
	s_waitcnt lgkmcnt(10)
	v_mfma_f32_16x16x32_bf16 v[34:37], v[210:213], v[82:85], v[34:37]
	v_exp_f32_e32 v118, v118
	v_mfma_f32_16x16x32_bf16 v[38:41], v[210:213], v[86:89], v[38:41]
	ds_read_b64_tr_b16 v[210:211], v238 offset:8192
	ds_read_b64_tr_b16 v[212:213], v238 offset:12288
	v_exp_f32_e32 v119, v119
	s_waitcnt lgkmcnt(10)
	v_mfma_f32_16x16x32_bf16 v[42:45], v[214:217], v[82:85], v[42:45]
	v_exp_f32_e32 v120, v120
	v_mfma_f32_16x16x32_bf16 v[46:49], v[214:217], v[86:89], v[46:49]
	ds_read_b64_tr_b16 v[214:215], v239 offset:8192
	ds_read_b64_tr_b16 v[216:217], v239 offset:12288
	v_exp_f32_e32 v121, v121
	s_waitcnt lgkmcnt(10)
	v_mfma_f32_16x16x32_bf16 v[50:53], v[218:221], v[82:85], v[50:53]
	v_exp_f32_e32 v122, v122
	v_mfma_f32_16x16x32_bf16 v[54:57], v[218:221], v[86:89], v[54:57]
	ds_read_b64_tr_b16 v[218:219], v240 offset:8192
	ds_read_b64_tr_b16 v[220:221], v240 offset:12288
	v_exp_f32_e32 v123, v123
	s_waitcnt lgkmcnt(10)
	v_mfma_f32_16x16x32_bf16 v[58:61], v[222:225], v[82:85], v[58:61]
	v_exp_f32_e32 v124, v124
	v_mfma_f32_16x16x32_bf16 v[62:65], v[222:225], v[86:89], v[62:65]
	ds_read_b64_tr_b16 v[222:223], v241 offset:8192
	ds_read_b64_tr_b16 v[224:225], v241 offset:12288
	v_exp_f32_e32 v125, v125
	s_waitcnt lgkmcnt(10)
	v_mfma_f32_16x16x32_bf16 v[66:69], v[202:205], v[82:85], v[66:69]
	v_exp_f32_e32 v126, v126
	v_mfma_f32_16x16x32_bf16 v[70:73], v[202:205], v[86:89], v[70:73]
	ds_read_b64_tr_b16 v[202:203], v242 offset:8192
	ds_read_b64_tr_b16 v[204:205], v242 offset:12288
	v_exp_f32_e32 v127, v127
	s_waitcnt lgkmcnt(10)
	v_mfma_f32_16x16x32_bf16 v[74:77], v[206:209], v[82:85], v[74:77]
	v_exp_f32_e32 v128, v128
	v_mfma_f32_16x16x32_bf16 v[78:81], v[206:209], v[86:89], v[78:81]
	ds_read_b64_tr_b16 v[206:207], v243 offset:8192
	ds_read_b64_tr_b16 v[208:209], v243 offset:12288
	v_exp_f32_e32 v129, v129
	s_waitcnt lgkmcnt(10)
	v_mfma_f32_16x16x32_bf16 v[18:21], v[210:213], v[98:101], v[18:21]
	v_exp_f32_e32 v130, v130
	v_mfma_f32_16x16x32_bf16 v[22:25], v[210:213], v[102:105], v[22:25]
	ds_read_b64_tr_b16 v[210:211], v244 offset:8192
	ds_read_b64_tr_b16 v[212:213], v244 offset:12288
	v_exp_f32_e32 v131, v131
	s_waitcnt lgkmcnt(10)
	v_mfma_f32_16x16x32_bf16 v[26:29], v[214:217], v[98:101], v[26:29]
	v_exp_f32_e32 v132, v132
	v_mfma_f32_16x16x32_bf16 v[30:33], v[214:217], v[102:105], v[30:33]
	ds_read_b64_tr_b16 v[214:215], v245 offset:8192
	ds_read_b64_tr_b16 v[216:217], v245 offset:12288
	v_exp_f32_e32 v133, v133
	s_waitcnt lgkmcnt(10)
	v_mfma_f32_16x16x32_bf16 v[34:37], v[218:221], v[98:101], v[34:37]
	v_exp_f32_e32 v134, v134
	v_mfma_f32_16x16x32_bf16 v[38:41], v[218:221], v[102:105], v[38:41]
	v_exp_f32_e32 v135, v135
	s_waitcnt lgkmcnt(8)
	v_mfma_f32_16x16x32_bf16 v[42:45], v[222:225], v[98:101], v[42:45]
	v_exp_f32_e32 v136, v136
	v_mfma_f32_16x16x32_bf16 v[46:49], v[222:225], v[102:105], v[46:49]
	v_exp_f32_e32 v137, v137
	s_waitcnt lgkmcnt(6)
	v_mfma_f32_16x16x32_bf16 v[50:53], v[202:205], v[98:101], v[50:53]
	v_exp_f32_e32 v138, v138
	ds_read_b128 v[178:181], v234 offset:32768
	v_mfma_f32_16x16x32_bf16 v[54:57], v[202:205], v[102:105], v[54:57]
	v_exp_f32_e32 v139, v139
	s_waitcnt lgkmcnt(5)
	v_mfma_f32_16x16x32_bf16 v[58:61], v[206:209], v[98:101], v[58:61]
	v_exp_f32_e32 v140, v140
	ds_read_b128 v[182:185], v234 offset:36864
	v_mfma_f32_16x16x32_bf16 v[62:65], v[206:209], v[102:105], v[62:65]
	v_exp_f32_e32 v141, v141
	s_waitcnt lgkmcnt(4)
	v_mfma_f32_16x16x32_bf16 v[66:69], v[210:213], v[98:101], v[66:69]
	v_exp_f32_e32 v142, v142
	ds_read_b128 v[186:189], v234 offset:40960
	v_mfma_f32_16x16x32_bf16 v[70:73], v[210:213], v[102:105], v[70:73]
	v_exp_f32_e32 v143, v143
	s_waitcnt lgkmcnt(3)
	v_mfma_f32_16x16x32_bf16 v[74:77], v[214:217], v[98:101], v[74:77]
	v_exp_f32_e32 v144, v144
	ds_read_b128 v[190:193], v234 offset:45056
	v_mfma_f32_16x16x32_bf16 v[78:81], v[214:217], v[102:105], v[78:81]
	v_exp_f32_e32 v145, v145
	s_waitcnt vmcnt(4)
	s_barrier
; __device__ __forceinline__ void finishSM(f32x16& p0, f32x16& p1, float& l_reg, bf16x8& pa0, bf16x8& pa1, bf16x8& pa2, bf16x8& pa3) {
;   for (int r = 0; r < 16; ++r) p1[r] = __builtin_amdgcn_exp2f(p1[r]);
;   float ps = 0; for (int r = 0; r < 16; ++r) ps += p0[r]; for (int r = 0; r < 16; ++r) ps += p1[r];
;   { auto rr = __builtin_amdgcn_permlane32_swap(__float_as_uint(ps), __float_as_uint(ps), false, false);
;     ps = __uint_as_float(rr[0]) + __uint_as_float(rr[1]); }
;   l_reg += ps;
;     ...
;   PK4(p0, 0, pa0); PK4(p0, 8, pa1); PK4(p1, 0, pa2); PK4(p1, 8, pa3);
;     ...
; }
; __device__ __forceinline__ void qkt(f32x16& p0, f32x16& p1, const bf16* Ks, const bf16x8* qr, int r32, int hi, const f32x16& negm) {
; #pragma unroll
;   for (int d0 = 0; d0 < 8; ++d0) { int cb = (d0 * 16 + hi * 8) * 2;
;     bf16x8 b0 = *reinterpret_cast<const bf16x8*>((const char*)Ks + KSWZ(r32, cb));
;     bf16x8 b1 = *reinterpret_cast<const bf16x8*>((const char*)Ks + KSWZ(32 + r32, cb));
;     if (d0 == 0) { p0 = __builtin_amdgcn_mfma_f32_32x32x16_bf16(b0, qr[0], negm, 0, 0, 0); p1 = __builtin_amdgcn_mfma_f32_32x32x16_bf16(b1, qr[0], negm, 0, 0, 0); }
;     else { p0 = __builtin_amdgcn_mfma_f32_32x32x16_bf16(b0, qr[d0], p0, 0, 0, 0); p1 = __builtin_amdgcn_mfma_f32_32x32x16_bf16(b1, qr[d0], p1, 0, 0, 0); } }
; }
	s_waitcnt lgkmcnt(3)
	v_mfma_f32_16x16x32_bf16 v[82:85], v[178:181], v[146:149], v[2:5]
	v_add_f32_e32 v250, v114, v250
	s_add_u32 s98, s98, 0x8000
	s_addc_u32 s99, s99, 0
	s_add_u32 s100, s100, 0x8000
	s_addc_u32 s101, s101, 0
	v_mfma_f32_16x16x32_bf16 v[86:89], v[178:181], v[162:165], v[2:5]
	ds_read_b128 v[178:181], v235 offset:32768
	v_add_f32_e32 v250, v115, v250
	v_add_f32_e32 v250, v116, v250
	s_waitcnt lgkmcnt(3)
	v_mfma_f32_16x16x32_bf16 v[90:93], v[182:185], v[146:149], v[2:5]
	v_add_f32_e32 v250, v117, v250
	v_mfma_f32_16x16x32_bf16 v[94:97], v[182:185], v[162:165], v[2:5]
	ds_read_b128 v[182:185], v235 offset:36864
	v_add_f32_e32 v250, v122, v250
	v_add_f32_e32 v250, v123, v250
	s_waitcnt lgkmcnt(3)
	v_mfma_f32_16x16x32_bf16 v[98:101], v[186:189], v[146:149], v[2:5]
	v_add_f32_e32 v250, v124, v250
	v_mfma_f32_16x16x32_bf16 v[102:105], v[186:189], v[162:165], v[2:5]
	ds_read_b128 v[186:189], v235 offset:40960
	v_add_f32_e32 v250, v125, v250
	v_cvt_pk_bf16_f32 v114, v114, v115
	s_waitcnt lgkmcnt(3)
	v_mfma_f32_16x16x32_bf16 v[106:109], v[190:193], v[146:149], v[2:5]
	v_cvt_pk_bf16_f32 v115, v116, v117
	s_add_u32 m0, s79, 16384
	s_nop 0
	global_load_lds_dwordx4 v246, s[98:99]
	v_mfma_f32_16x16x32_bf16 v[110:113], v[190:193], v[162:165], v[2:5]
	ds_read_b128 v[190:193], v235 offset:45056
	v_cvt_pk_bf16_f32 v116, v122, v123
	v_cvt_pk_bf16_f32 v117, v124, v125
	s_waitcnt lgkmcnt(3)
	v_mfma_f32_16x16x32_bf16 v[82:85], v[178:181], v[150:153], v[82:85]
	v_add_f32_e32 v251, v118, v251
	v_mfma_f32_16x16x32_bf16 v[86:89], v[178:181], v[166:169], v[86:89]
	ds_read_b128 v[178:181], v236 offset:32768
	v_add_f32_e32 v251, v119, v251
	v_add_f32_e32 v251, v120, v251
	s_waitcnt lgkmcnt(3)
	v_mfma_f32_16x16x32_bf16 v[90:93], v[182:185], v[150:153], v[90:93]
	v_add_f32_e32 v251, v121, v251
	v_mfma_f32_16x16x32_bf16 v[94:97], v[182:185], v[166:169], v[94:97]
	ds_read_b128 v[182:185], v236 offset:36864
	v_add_f32_e32 v251, v126, v251
	v_add_f32_e32 v251, v127, v251
	s_waitcnt lgkmcnt(3)
	v_mfma_f32_16x16x32_bf16 v[98:101], v[186:189], v[150:153], v[98:101]
	v_add_f32_e32 v251, v128, v251
	v_mfma_f32_16x16x32_bf16 v[102:105], v[186:189], v[166:169], v[102:105]
	ds_read_b128 v[186:189], v236 offset:40960
	v_add_f32_e32 v251, v129, v251
	v_cvt_pk_bf16_f32 v118, v118, v119
	s_waitcnt lgkmcnt(3)
	v_mfma_f32_16x16x32_bf16 v[106:109], v[190:193], v[150:153], v[106:109]
	v_cvt_pk_bf16_f32 v119, v120, v121
	s_add_u32 m0, s79, 17408
	s_nop 0
	global_load_lds_dwordx4 v247, s[98:99]
	v_mfma_f32_16x16x32_bf16 v[110:113], v[190:193], v[166:169], v[110:113]
	ds_read_b128 v[190:193], v236 offset:45056
	v_cvt_pk_bf16_f32 v120, v126, v127
	v_cvt_pk_bf16_f32 v121, v128, v129
	s_waitcnt lgkmcnt(3)
	v_mfma_f32_16x16x32_bf16 v[82:85], v[178:181], v[154:157], v[82:85]
	v_add_f32_e32 v250, v130, v250
	v_mfma_f32_16x16x32_bf16 v[86:89], v[178:181], v[170:173], v[86:89]
	ds_read_b128 v[178:181], v237 offset:32768
	v_add_f32_e32 v250, v131, v250
	v_add_f32_e32 v250, v132, v250
	s_waitcnt lgkmcnt(3)
	v_mfma_f32_16x16x32_bf16 v[90:93], v[182:185], v[154:157], v[90:93]
	v_add_f32_e32 v250, v133, v250
	v_mfma_f32_16x16x32_bf16 v[94:97], v[182:185], v[170:173], v[94:97]
	ds_read_b128 v[182:185], v237 offset:36864
	v_add_f32_e32 v250, v138, v250
	v_add_f32_e32 v250, v139, v250
	s_waitcnt lgkmcnt(3)
	v_mfma_f32_16x16x32_bf16 v[98:101], v[186:189], v[154:157], v[98:101]
	v_add_f32_e32 v250, v140, v250
	ds_read_b64_tr_b16 v[202:203], v238 offset:16384
	ds_read_b64_tr_b16 v[204:205], v238 offset:20480
	v_mfma_f32_16x16x32_bf16 v[102:105], v[186:189], v[170:173], v[102:105]
	ds_read_b128 v[186:189], v237 offset:40960
	v_add_f32_e32 v250, v141, v250
	v_cvt_pk_bf16_f32 v130, v130, v131
	s_waitcnt lgkmcnt(5)
	v_mfma_f32_16x16x32_bf16 v[106:109], v[190:193], v[154:157], v[106:109]
	v_cvt_pk_bf16_f32 v131, v132, v133
	s_add_u32 m0, s80, 0
	s_nop 0
	global_load_lds_dwordx4 v248, s[100:101]
	ds_read_b64_tr_b16 v[206:207], v239 offset:16384
	ds_read_b64_tr_b16 v[208:209], v239 offset:20480
	v_mfma_f32_16x16x32_bf16 v[110:113], v[190:193], v[170:173], v[110:113]
	ds_read_b128 v[190:193], v237 offset:45056
	v_cvt_pk_bf16_f32 v132, v138, v139
	v_cvt_pk_bf16_f32 v133, v140, v141
	s_waitcnt lgkmcnt(7)
	v_mfma_f32_16x16x32_bf16 v[82:85], v[178:181], v[158:161], v[82:85]
	v_add_f32_e32 v251, v134, v251
	ds_read_b64_tr_b16 v[210:211], v240 offset:16384
	ds_read_b64_tr_b16 v[212:213], v240 offset:20480
	v_mfma_f32_16x16x32_bf16 v[86:89], v[178:181], v[174:177], v[86:89]
	v_add_f32_e32 v251, v135, v251
	v_add_f32_e32 v251, v136, v251
	s_waitcnt lgkmcnt(8)
	v_mfma_f32_16x16x32_bf16 v[90:93], v[182:185], v[158:161], v[90:93]
	v_add_f32_e32 v251, v137, v251
	ds_read_b64_tr_b16 v[214:215], v241 offset:16384
	ds_read_b64_tr_b16 v[216:217], v241 offset:20480
	v_mfma_f32_16x16x32_bf16 v[94:97], v[182:185], v[174:177], v[94:97]
	v_add_f32_e32 v251, v142, v251
	v_add_f32_e32 v251, v143, v251
	s_waitcnt lgkmcnt(7)
	v_mfma_f32_16x16x32_bf16 v[98:101], v[186:189], v[158:161], v[98:101]
	v_add_f32_e32 v251, v144, v251
	ds_read_b64_tr_b16 v[218:219], v242 offset:16384
	ds_read_b64_tr_b16 v[220:221], v242 offset:20480
	v_mfma_f32_16x16x32_bf16 v[102:105], v[186:189], v[174:177], v[102:105]
	v_add_f32_e32 v251, v145, v251
	v_cvt_pk_bf16_f32 v134, v134, v135
	s_waitcnt lgkmcnt(6)
; #define SBAR() __builtin_amdgcn_sched_barrier(0)
; __device__ __forceinline__ void qkt(f32x16& p0, f32x16& p1, const bf16* Ks, const bf16x8* qr, int r32, int hi, const f32x16& negm) {
; #pragma unroll
;   for (int d0 = 0; d0 < 8; ++d0) { int cb = (d0 * 16 + hi * 8) * 2;
;     bf16x8 b0 = *reinterpret_cast<const bf16x8*>((const char*)Ks + KSWZ(r32, cb));
;     bf16x8 b1 = *reinterpret_cast<const bf16x8*>((const char*)Ks + KSWZ(32 + r32, cb));
;     if (d0 == 0) { p0 = __builtin_amdgcn_mfma_f32_32x32x16_bf16(b0, qr[0], negm, 0, 0, 0); p1 = __builtin_amdgcn_mfma_f32_32x32x16_bf16(b1, qr[0], negm, 0, 0, 0); }
;     else { p0 = __builtin_amdgcn_mfma_f32_32x32x16_bf16(b0, qr[d0], p0, 0, 0, 0); p1 = __builtin_amdgcn_mfma_f32_32x32x16_bf16(b1, qr[d0], p1, 0, 0, 0); } }
; }
; template <int D0> __device__ __forceinline__ void pv_one(f32x16& od, int vb, bf16x8 pa0, bf16x8 pa1, bf16x8 pa2, bf16x8 pa3) {
;   const s16x4 l0 = tr_read<v_rd_off(D0, 0, 0)>(vb), h0 = tr_read<v_rd_off(D0, 0, 1)>(vb), l1 = tr_read<v_rd_off(D0, 1, 0)>(vb), h1 = tr_read<v_rd_off(D0, 1, 1)>(vb);
;   const s16x4 l2 = tr_read<v_rd_off(D0, 2, 0)>(vb), h2 = tr_read<v_rd_off(D0, 2, 1)>(vb), l3 = tr_read<v_rd_off(D0, 3, 0)>(vb), h3 = tr_read<v_rd_off(D0, 3, 1)>(vb);
;   asm volatile("s_waitcnt lgkmcnt(0)" ::: "memory"); SBAR();
;     ...
;   od = __builtin_amdgcn_mfma_f32_32x32x16_bf16(pa0, PK(l0, h0), od, 0, 0, 0);
;   od = __builtin_amdgcn_mfma_f32_32x32x16_bf16(pa1, PK(l1, h1), od, 0, 0, 0);
;   od = __builtin_amdgcn_mfma_f32_32x32x16_bf16(pa2, PK(l2, h2), od, 0, 0, 0);
;   od = __builtin_amdgcn_mfma_f32_32x32x16_bf16(pa3, PK(l3, h3), od, 0, 0, 0);
;     ...
; }
; __device__ __forceinline__ void pv_d0(f32x16* o, int vb, bf16x8 pa0, bf16x8 pa1, bf16x8 pa2, bf16x8 pa3) {
;   pv_one<0>(o[0], vb, pa0, pa1, pa2, pa3); pv_one<1>(o[1], vb, pa0, pa1, pa2, pa3); pv_one<2>(o[2], vb, pa0, pa1, pa2, pa3); pv_one<3>(o[3], vb, pa0, pa1, pa2, pa3);
	v_mfma_f32_16x16x32_bf16 v[106:109], v[190:193], v[158:161], v[106:109]
	v_cvt_pk_bf16_f32 v135, v136, v137
	s_add_u32 m0, s80, 1024
	s_nop 0
	global_load_lds_dwordx4 v249, s[100:101]
	ds_read_b64_tr_b16 v[222:223], v243 offset:16384
	ds_read_b64_tr_b16 v[224:225], v243 offset:20480
	v_mfma_f32_16x16x32_bf16 v[110:113], v[190:193], v[174:177], v[110:113]
	v_cvt_pk_bf16_f32 v136, v142, v143
	v_cvt_pk_bf16_f32 v137, v144, v145
	v_mfma_f32_16x16x32_bf16 v[18:21], v[202:205], v[114:117], v[18:21]
	v_exp_f32_e32 v82, v82
	v_mfma_f32_16x16x32_bf16 v[22:25], v[202:205], v[118:121], v[22:25]
	ds_read_b64_tr_b16 v[202:203], v244 offset:16384
	ds_read_b64_tr_b16 v[204:205], v244 offset:20480
	v_exp_f32_e32 v83, v83
	v_mfma_f32_16x16x32_bf16 v[26:29], v[206:209], v[114:117], v[26:29]
	v_exp_f32_e32 v84, v84
	v_mfma_f32_16x16x32_bf16 v[30:33], v[206:209], v[118:121], v[30:33]
	ds_read_b64_tr_b16 v[206:207], v245 offset:16384
	ds_read_b64_tr_b16 v[208:209], v245 offset:20480
	v_exp_f32_e32 v85, v85
	s_waitcnt lgkmcnt(10)
	v_mfma_f32_16x16x32_bf16 v[34:37], v[210:213], v[114:117], v[34:37]
	v_exp_f32_e32 v86, v86
	v_mfma_f32_16x16x32_bf16 v[38:41], v[210:213], v[118:121], v[38:41]
	ds_read_b64_tr_b16 v[210:211], v238 offset:24576
	ds_read_b64_tr_b16 v[212:213], v238 offset:28672
	v_exp_f32_e32 v87, v87
	s_waitcnt lgkmcnt(10)
	v_mfma_f32_16x16x32_bf16 v[42:45], v[214:217], v[114:117], v[42:45]
	v_exp_f32_e32 v88, v88
	v_mfma_f32_16x16x32_bf16 v[46:49], v[214:217], v[118:121], v[46:49]
	ds_read_b64_tr_b16 v[214:215], v239 offset:24576
	ds_read_b64_tr_b16 v[216:217], v239 offset:28672
	v_exp_f32_e32 v89, v89
	s_waitcnt lgkmcnt(10)
	v_mfma_f32_16x16x32_bf16 v[50:53], v[218:221], v[114:117], v[50:53]
	v_exp_f32_e32 v90, v90
	v_mfma_f32_16x16x32_bf16 v[54:57], v[218:221], v[118:121], v[54:57]
	ds_read_b64_tr_b16 v[218:219], v240 offset:24576
	ds_read_b64_tr_b16 v[220:221], v240 offset:28672
	v_exp_f32_e32 v91, v91
	s_waitcnt lgkmcnt(10)
	v_mfma_f32_16x16x32_bf16 v[58:61], v[222:225], v[114:117], v[58:61]
	v_exp_f32_e32 v92, v92
	v_mfma_f32_16x16x32_bf16 v[62:65], v[222:225], v[118:121], v[62:65]
	ds_read_b64_tr_b16 v[222:223], v241 offset:24576
	ds_read_b64_tr_b16 v[224:225], v241 offset:28672
	v_exp_f32_e32 v93, v93
	s_waitcnt lgkmcnt(10)
	v_mfma_f32_16x16x32_bf16 v[66:69], v[202:205], v[114:117], v[66:69]
	v_exp_f32_e32 v94, v94
	v_mfma_f32_16x16x32_bf16 v[70:73], v[202:205], v[118:121], v[70:73]
	ds_read_b64_tr_b16 v[202:203], v242 offset:24576
	ds_read_b64_tr_b16 v[204:205], v242 offset:28672
	v_exp_f32_e32 v95, v95
	s_waitcnt lgkmcnt(10)
	v_mfma_f32_16x16x32_bf16 v[74:77], v[206:209], v[114:117], v[74:77]
	v_exp_f32_e32 v96, v96
	v_mfma_f32_16x16x32_bf16 v[78:81], v[206:209], v[118:121], v[78:81]
	ds_read_b64_tr_b16 v[206:207], v243 offset:24576
	ds_read_b64_tr_b16 v[208:209], v243 offset:28672
	v_exp_f32_e32 v97, v97
	s_waitcnt lgkmcnt(10)
	v_mfma_f32_16x16x32_bf16 v[18:21], v[210:213], v[130:133], v[18:21]
	v_exp_f32_e32 v98, v98
	v_mfma_f32_16x16x32_bf16 v[22:25], v[210:213], v[134:137], v[22:25]
	ds_read_b64_tr_b16 v[210:211], v244 offset:24576
	ds_read_b64_tr_b16 v[212:213], v244 offset:28672
	v_exp_f32_e32 v99, v99
	s_waitcnt lgkmcnt(10)
	v_mfma_f32_16x16x32_bf16 v[26:29], v[214:217], v[130:133], v[26:29]
	v_exp_f32_e32 v100, v100
	v_mfma_f32_16x16x32_bf16 v[30:33], v[214:217], v[134:137], v[30:33]
	ds_read_b64_tr_b16 v[214:215], v245 offset:24576
	ds_read_b64_tr_b16 v[216:217], v245 offset:28672
	v_exp_f32_e32 v101, v101
	s_waitcnt lgkmcnt(10)
	v_mfma_f32_16x16x32_bf16 v[34:37], v[218:221], v[130:133], v[34:37]
	v_exp_f32_e32 v102, v102
	v_mfma_f32_16x16x32_bf16 v[38:41], v[218:221], v[134:137], v[38:41]
	v_exp_f32_e32 v103, v103
	s_waitcnt lgkmcnt(8)
	v_mfma_f32_16x16x32_bf16 v[42:45], v[222:225], v[130:133], v[42:45]
	v_exp_f32_e32 v104, v104
	v_mfma_f32_16x16x32_bf16 v[46:49], v[222:225], v[134:137], v[46:49]
	v_exp_f32_e32 v105, v105
	s_waitcnt lgkmcnt(6)
	v_mfma_f32_16x16x32_bf16 v[50:53], v[202:205], v[130:133], v[50:53]
	v_exp_f32_e32 v106, v106
	ds_read_b128 v[178:181], v234 offset:49152
	v_mfma_f32_16x16x32_bf16 v[54:57], v[202:205], v[134:137], v[54:57]
	v_exp_f32_e32 v107, v107
	s_waitcnt lgkmcnt(5)
	v_mfma_f32_16x16x32_bf16 v[58:61], v[206:209], v[130:133], v[58:61]
	v_exp_f32_e32 v108, v108
	ds_read_b128 v[182:185], v234 offset:53248
	v_mfma_f32_16x16x32_bf16 v[62:65], v[206:209], v[134:137], v[62:65]
	v_exp_f32_e32 v109, v109
	s_waitcnt lgkmcnt(4)
	v_mfma_f32_16x16x32_bf16 v[66:69], v[210:213], v[130:133], v[66:69]
	v_exp_f32_e32 v110, v110
	ds_read_b128 v[186:189], v234 offset:57344
	v_mfma_f32_16x16x32_bf16 v[70:73], v[210:213], v[134:137], v[70:73]
	v_exp_f32_e32 v111, v111
	s_waitcnt lgkmcnt(3)
	v_mfma_f32_16x16x32_bf16 v[74:77], v[214:217], v[130:133], v[74:77]
	v_exp_f32_e32 v112, v112
	ds_read_b128 v[190:193], v234 offset:61440
	v_mfma_f32_16x16x32_bf16 v[78:81], v[214:217], v[134:137], v[78:81]
	v_exp_f32_e32 v113, v113
	s_waitcnt vmcnt(4)
	s_barrier
; __device__ __forceinline__ void finishSM(f32x16& p0, f32x16& p1, float& l_reg, bf16x8& pa0, bf16x8& pa1, bf16x8& pa2, bf16x8& pa3) {
;   for (int r = 0; r < 16; ++r) p1[r] = __builtin_amdgcn_exp2f(p1[r]);
;   float ps = 0; for (int r = 0; r < 16; ++r) ps += p0[r]; for (int r = 0; r < 16; ++r) ps += p1[r];
;   { auto rr = __builtin_amdgcn_permlane32_swap(__float_as_uint(ps), __float_as_uint(ps), false, false);
;     ps = __uint_as_float(rr[0]) + __uint_as_float(rr[1]); }
;   l_reg += ps;
;     ...
;   PK4(p0, 0, pa0); PK4(p0, 8, pa1); PK4(p1, 0, pa2); PK4(p1, 8, pa3);
;     ...
; }
; __device__ __forceinline__ void qkt(f32x16& p0, f32x16& p1, const bf16* Ks, const bf16x8* qr, int r32, int hi, const f32x16& negm) {
; #pragma unroll
;   for (int d0 = 0; d0 < 8; ++d0) { int cb = (d0 * 16 + hi * 8) * 2;
;     bf16x8 b0 = *reinterpret_cast<const bf16x8*>((const char*)Ks + KSWZ(r32, cb));
;     bf16x8 b1 = *reinterpret_cast<const bf16x8*>((const char*)Ks + KSWZ(32 + r32, cb));
;     if (d0 == 0) { p0 = __builtin_amdgcn_mfma_f32_32x32x16_bf16(b0, qr[0], negm, 0, 0, 0); p1 = __builtin_amdgcn_mfma_f32_32x32x16_bf16(b1, qr[0], negm, 0, 0, 0); }
;     else { p0 = __builtin_amdgcn_mfma_f32_32x32x16_bf16(b0, qr[d0], p0, 0, 0, 0); p1 = __builtin_amdgcn_mfma_f32_32x32x16_bf16(b1, qr[d0], p1, 0, 0, 0); } }
; }
	s_waitcnt lgkmcnt(3)
	v_mfma_f32_16x16x32_bf16 v[114:117], v[178:181], v[146:149], v[2:5]
	v_add_f32_e32 v250, v82, v250
	s_add_u32 s98, s98, 0x8000
	s_addc_u32 s99, s99, 0
	s_add_u32 s100, s100, 0x8000
	s_addc_u32 s101, s101, 0
	v_mfma_f32_16x16x32_bf16 v[118:121], v[178:181], v[162:165], v[2:5]
	ds_read_b128 v[178:181], v235 offset:49152
	v_add_f32_e32 v250, v83, v250
	v_add_f32_e32 v250, v84, v250
	s_waitcnt lgkmcnt(3)
	v_mfma_f32_16x16x32_bf16 v[122:125], v[182:185], v[146:149], v[2:5]
	v_add_f32_e32 v250, v85, v250
	v_mfma_f32_16x16x32_bf16 v[126:129], v[182:185], v[162:165], v[2:5]
	ds_read_b128 v[182:185], v235 offset:53248
	v_add_f32_e32 v250, v90, v250
	v_add_f32_e32 v250, v91, v250
	s_waitcnt lgkmcnt(3)
	v_mfma_f32_16x16x32_bf16 v[130:133], v[186:189], v[146:149], v[2:5]
	v_add_f32_e32 v250, v92, v250
	v_mfma_f32_16x16x32_bf16 v[134:137], v[186:189], v[162:165], v[2:5]
	ds_read_b128 v[186:189], v235 offset:57344
	v_add_f32_e32 v250, v93, v250
	v_cvt_pk_bf16_f32 v82, v82, v83
	s_waitcnt lgkmcnt(3)
	v_mfma_f32_16x16x32_bf16 v[138:141], v[190:193], v[146:149], v[2:5]
	v_cvt_pk_bf16_f32 v83, v84, v85
	s_add_u32 m0, s79, 32768
	s_nop 0
	global_load_lds_dwordx4 v246, s[98:99]
	v_mfma_f32_16x16x32_bf16 v[142:145], v[190:193], v[162:165], v[2:5]
	ds_read_b128 v[190:193], v235 offset:61440
	v_cvt_pk_bf16_f32 v84, v90, v91
	v_cvt_pk_bf16_f32 v85, v92, v93
	s_waitcnt lgkmcnt(3)
	v_mfma_f32_16x16x32_bf16 v[114:117], v[178:181], v[150:153], v[114:117]
	v_add_f32_e32 v251, v86, v251
	v_mfma_f32_16x16x32_bf16 v[118:121], v[178:181], v[166:169], v[118:121]
	ds_read_b128 v[178:181], v236 offset:49152
	v_add_f32_e32 v251, v87, v251
	v_add_f32_e32 v251, v88, v251
	s_waitcnt lgkmcnt(3)
	v_mfma_f32_16x16x32_bf16 v[122:125], v[182:185], v[150:153], v[122:125]
	v_add_f32_e32 v251, v89, v251
	v_mfma_f32_16x16x32_bf16 v[126:129], v[182:185], v[166:169], v[126:129]
	ds_read_b128 v[182:185], v236 offset:53248
	v_add_f32_e32 v251, v94, v251
	v_add_f32_e32 v251, v95, v251
	s_waitcnt lgkmcnt(3)
	v_mfma_f32_16x16x32_bf16 v[130:133], v[186:189], v[150:153], v[130:133]
	v_add_f32_e32 v251, v96, v251
	v_mfma_f32_16x16x32_bf16 v[134:137], v[186:189], v[166:169], v[134:137]
	ds_read_b128 v[186:189], v236 offset:57344
	v_add_f32_e32 v251, v97, v251
	v_cvt_pk_bf16_f32 v86, v86, v87
	s_waitcnt lgkmcnt(3)
	v_mfma_f32_16x16x32_bf16 v[138:141], v[190:193], v[150:153], v[138:141]
	v_cvt_pk_bf16_f32 v87, v88, v89
	s_add_u32 m0, s79, 33792
	s_nop 0
	global_load_lds_dwordx4 v247, s[98:99]
	v_mfma_f32_16x16x32_bf16 v[142:145], v[190:193], v[166:169], v[142:145]
	ds_read_b128 v[190:193], v236 offset:61440
	v_cvt_pk_bf16_f32 v88, v94, v95
	v_cvt_pk_bf16_f32 v89, v96, v97
	s_waitcnt lgkmcnt(3)
	v_mfma_f32_16x16x32_bf16 v[114:117], v[178:181], v[154:157], v[114:117]
	v_add_f32_e32 v250, v98, v250
	v_mfma_f32_16x16x32_bf16 v[118:121], v[178:181], v[170:173], v[118:121]
	ds_read_b128 v[178:181], v237 offset:49152
	v_add_f32_e32 v250, v99, v250
	v_add_f32_e32 v250, v100, v250
	s_waitcnt lgkmcnt(3)
	v_mfma_f32_16x16x32_bf16 v[122:125], v[182:185], v[154:157], v[122:125]
	v_add_f32_e32 v250, v101, v250
	v_mfma_f32_16x16x32_bf16 v[126:129], v[182:185], v[170:173], v[126:129]
	ds_read_b128 v[182:185], v237 offset:53248
	v_add_f32_e32 v250, v106, v250
	v_add_f32_e32 v250, v107, v250
	s_waitcnt lgkmcnt(3)
	v_mfma_f32_16x16x32_bf16 v[130:133], v[186:189], v[154:157], v[130:133]
	v_add_f32_e32 v250, v108, v250
	ds_read_b64_tr_b16 v[202:203], v238 offset:32768
	ds_read_b64_tr_b16 v[204:205], v238 offset:36864
	v_mfma_f32_16x16x32_bf16 v[134:137], v[186:189], v[170:173], v[134:137]
	ds_read_b128 v[186:189], v237 offset:57344
	v_add_f32_e32 v250, v109, v250
	v_cvt_pk_bf16_f32 v98, v98, v99
	s_waitcnt lgkmcnt(5)
	v_mfma_f32_16x16x32_bf16 v[138:141], v[190:193], v[154:157], v[138:141]
	v_cvt_pk_bf16_f32 v99, v100, v101
	s_add_u32 m0, s80, 16384
	s_nop 0
	global_load_lds_dwordx4 v248, s[100:101]
	ds_read_b64_tr_b16 v[206:207], v239 offset:32768
	ds_read_b64_tr_b16 v[208:209], v239 offset:36864
	v_mfma_f32_16x16x32_bf16 v[142:145], v[190:193], v[170:173], v[142:145]
	ds_read_b128 v[190:193], v237 offset:61440
	v_cvt_pk_bf16_f32 v100, v106, v107
	v_cvt_pk_bf16_f32 v101, v108, v109
	s_waitcnt lgkmcnt(7)
	v_mfma_f32_16x16x32_bf16 v[114:117], v[178:181], v[158:161], v[114:117]
	v_add_f32_e32 v251, v102, v251
	ds_read_b64_tr_b16 v[210:211], v240 offset:32768
	ds_read_b64_tr_b16 v[212:213], v240 offset:36864
	v_mfma_f32_16x16x32_bf16 v[118:121], v[178:181], v[174:177], v[118:121]
	v_add_f32_e32 v251, v103, v251
	v_add_f32_e32 v251, v104, v251
	s_waitcnt lgkmcnt(8)
	v_mfma_f32_16x16x32_bf16 v[122:125], v[182:185], v[158:161], v[122:125]
	v_add_f32_e32 v251, v105, v251
	ds_read_b64_tr_b16 v[214:215], v241 offset:32768
	ds_read_b64_tr_b16 v[216:217], v241 offset:36864
	v_mfma_f32_16x16x32_bf16 v[126:129], v[182:185], v[174:177], v[126:129]
	v_add_f32_e32 v251, v110, v251
	v_add_f32_e32 v251, v111, v251
	s_waitcnt lgkmcnt(7)
	v_mfma_f32_16x16x32_bf16 v[130:133], v[186:189], v[158:161], v[130:133]
	v_add_f32_e32 v251, v112, v251
	ds_read_b64_tr_b16 v[218:219], v242 offset:32768
	ds_read_b64_tr_b16 v[220:221], v242 offset:36864
	v_mfma_f32_16x16x32_bf16 v[134:137], v[186:189], v[174:177], v[134:137]
	v_add_f32_e32 v251, v113, v251
	v_cvt_pk_bf16_f32 v102, v102, v103
	s_waitcnt lgkmcnt(6)
; #define SBAR() __builtin_amdgcn_sched_barrier(0)
; __device__ __forceinline__ void qkt(f32x16& p0, f32x16& p1, const bf16* Ks, const bf16x8* qr, int r32, int hi, const f32x16& negm) {
; #pragma unroll
;   for (int d0 = 0; d0 < 8; ++d0) { int cb = (d0 * 16 + hi * 8) * 2;
;     bf16x8 b0 = *reinterpret_cast<const bf16x8*>((const char*)Ks + KSWZ(r32, cb));
;     bf16x8 b1 = *reinterpret_cast<const bf16x8*>((const char*)Ks + KSWZ(32 + r32, cb));
;     if (d0 == 0) { p0 = __builtin_amdgcn_mfma_f32_32x32x16_bf16(b0, qr[0], negm, 0, 0, 0); p1 = __builtin_amdgcn_mfma_f32_32x32x16_bf16(b1, qr[0], negm, 0, 0, 0); }
;     else { p0 = __builtin_amdgcn_mfma_f32_32x32x16_bf16(b0, qr[d0], p0, 0, 0, 0); p1 = __builtin_amdgcn_mfma_f32_32x32x16_bf16(b1, qr[d0], p1, 0, 0, 0); } }
; }
; template <int D0> __device__ __forceinline__ void pv_one(f32x16& od, int vb, bf16x8 pa0, bf16x8 pa1, bf16x8 pa2, bf16x8 pa3) {
;   const s16x4 l0 = tr_read<v_rd_off(D0, 0, 0)>(vb), h0 = tr_read<v_rd_off(D0, 0, 1)>(vb), l1 = tr_read<v_rd_off(D0, 1, 0)>(vb), h1 = tr_read<v_rd_off(D0, 1, 1)>(vb);
;   const s16x4 l2 = tr_read<v_rd_off(D0, 2, 0)>(vb), h2 = tr_read<v_rd_off(D0, 2, 1)>(vb), l3 = tr_read<v_rd_off(D0, 3, 0)>(vb), h3 = tr_read<v_rd_off(D0, 3, 1)>(vb);
;   asm volatile("s_waitcnt lgkmcnt(0)" ::: "memory"); SBAR();
;     ...
;   od = __builtin_amdgcn_mfma_f32_32x32x16_bf16(pa0, PK(l0, h0), od, 0, 0, 0);
;   od = __builtin_amdgcn_mfma_f32_32x32x16_bf16(pa1, PK(l1, h1), od, 0, 0, 0);
;   od = __builtin_amdgcn_mfma_f32_32x32x16_bf16(pa2, PK(l2, h2), od, 0, 0, 0);
;   od = __builtin_amdgcn_mfma_f32_32x32x16_bf16(pa3, PK(l3, h3), od, 0, 0, 0);
;     ...
; }
; __device__ __forceinline__ void pv_d0(f32x16* o, int vb, bf16x8 pa0, bf16x8 pa1, bf16x8 pa2, bf16x8 pa3) {
;   pv_one<0>(o[0], vb, pa0, pa1, pa2, pa3); pv_one<1>(o[1], vb, pa0, pa1, pa2, pa3); pv_one<2>(o[2], vb, pa0, pa1, pa2, pa3); pv_one<3>(o[3], vb, pa0, pa1, pa2, pa3);
	v_mfma_f32_16x16x32_bf16 v[138:141], v[190:193], v[158:161], v[138:141]
	v_cvt_pk_bf16_f32 v103, v104, v105
	s_add_u32 m0, s80, 17408
	s_nop 0
	global_load_lds_dwordx4 v249, s[100:101]
	ds_read_b64_tr_b16 v[222:223], v243 offset:32768
	ds_read_b64_tr_b16 v[224:225], v243 offset:36864
	v_mfma_f32_16x16x32_bf16 v[142:145], v[190:193], v[174:177], v[142:145]
	v_cvt_pk_bf16_f32 v104, v110, v111
	v_cvt_pk_bf16_f32 v105, v112, v113
	v_mfma_f32_16x16x32_bf16 v[18:21], v[202:205], v[82:85], v[18:21]
	v_exp_f32_e32 v114, v114
	v_mfma_f32_16x16x32_bf16 v[22:25], v[202:205], v[86:89], v[22:25]
	ds_read_b64_tr_b16 v[202:203], v244 offset:32768
	ds_read_b64_tr_b16 v[204:205], v244 offset:36864
	v_exp_f32_e32 v115, v115
	v_mfma_f32_16x16x32_bf16 v[26:29], v[206:209], v[82:85], v[26:29]
	v_exp_f32_e32 v116, v116
	v_mfma_f32_16x16x32_bf16 v[30:33], v[206:209], v[86:89], v[30:33]
	ds_read_b64_tr_b16 v[206:207], v245 offset:32768
	ds_read_b64_tr_b16 v[208:209], v245 offset:36864
	v_exp_f32_e32 v117, v117
	s_waitcnt lgkmcnt(10)
	v_mfma_f32_16x16x32_bf16 v[34:37], v[210:213], v[82:85], v[34:37]
	v_exp_f32_e32 v118, v118
	v_mfma_f32_16x16x32_bf16 v[38:41], v[210:213], v[86:89], v[38:41]
	ds_read_b64_tr_b16 v[210:211], v238 offset:40960
	ds_read_b64_tr_b16 v[212:213], v238 offset:45056
	v_exp_f32_e32 v119, v119
	s_waitcnt lgkmcnt(10)
	v_mfma_f32_16x16x32_bf16 v[42:45], v[214:217], v[82:85], v[42:45]
	v_exp_f32_e32 v120, v120
	v_mfma_f32_16x16x32_bf16 v[46:49], v[214:217], v[86:89], v[46:49]
	ds_read_b64_tr_b16 v[214:215], v239 offset:40960
	ds_read_b64_tr_b16 v[216:217], v239 offset:45056
	v_exp_f32_e32 v121, v121
	s_waitcnt lgkmcnt(10)
	v_mfma_f32_16x16x32_bf16 v[50:53], v[218:221], v[82:85], v[50:53]
	v_exp_f32_e32 v122, v122
	v_mfma_f32_16x16x32_bf16 v[54:57], v[218:221], v[86:89], v[54:57]
	ds_read_b64_tr_b16 v[218:219], v240 offset:40960
	ds_read_b64_tr_b16 v[220:221], v240 offset:45056
	v_exp_f32_e32 v123, v123
	s_waitcnt lgkmcnt(10)
	v_mfma_f32_16x16x32_bf16 v[58:61], v[222:225], v[82:85], v[58:61]
	v_exp_f32_e32 v124, v124
	v_mfma_f32_16x16x32_bf16 v[62:65], v[222:225], v[86:89], v[62:65]
	ds_read_b64_tr_b16 v[222:223], v241 offset:40960
	ds_read_b64_tr_b16 v[224:225], v241 offset:45056
	v_exp_f32_e32 v125, v125
	s_waitcnt lgkmcnt(10)
	v_mfma_f32_16x16x32_bf16 v[66:69], v[202:205], v[82:85], v[66:69]
	v_exp_f32_e32 v126, v126
	v_mfma_f32_16x16x32_bf16 v[70:73], v[202:205], v[86:89], v[70:73]
	ds_read_b64_tr_b16 v[202:203], v242 offset:40960
	ds_read_b64_tr_b16 v[204:205], v242 offset:45056
	v_exp_f32_e32 v127, v127
	s_waitcnt lgkmcnt(10)
	v_mfma_f32_16x16x32_bf16 v[74:77], v[206:209], v[82:85], v[74:77]
	v_exp_f32_e32 v128, v128
	v_mfma_f32_16x16x32_bf16 v[78:81], v[206:209], v[86:89], v[78:81]
	ds_read_b64_tr_b16 v[206:207], v243 offset:40960
	ds_read_b64_tr_b16 v[208:209], v243 offset:45056
	v_exp_f32_e32 v129, v129
	s_waitcnt lgkmcnt(10)
	v_mfma_f32_16x16x32_bf16 v[18:21], v[210:213], v[98:101], v[18:21]
	v_exp_f32_e32 v130, v130
	v_mfma_f32_16x16x32_bf16 v[22:25], v[210:213], v[102:105], v[22:25]
	ds_read_b64_tr_b16 v[210:211], v244 offset:40960
	ds_read_b64_tr_b16 v[212:213], v244 offset:45056
	v_exp_f32_e32 v131, v131
	s_waitcnt lgkmcnt(10)
	v_mfma_f32_16x16x32_bf16 v[26:29], v[214:217], v[98:101], v[26:29]
	v_exp_f32_e32 v132, v132
	v_mfma_f32_16x16x32_bf16 v[30:33], v[214:217], v[102:105], v[30:33]
	ds_read_b64_tr_b16 v[214:215], v245 offset:40960
	ds_read_b64_tr_b16 v[216:217], v245 offset:45056
	v_exp_f32_e32 v133, v133
	s_waitcnt lgkmcnt(10)
	v_mfma_f32_16x16x32_bf16 v[34:37], v[218:221], v[98:101], v[34:37]
	v_exp_f32_e32 v134, v134
	v_mfma_f32_16x16x32_bf16 v[38:41], v[218:221], v[102:105], v[38:41]
	v_exp_f32_e32 v135, v135
	s_waitcnt lgkmcnt(8)
	v_mfma_f32_16x16x32_bf16 v[42:45], v[222:225], v[98:101], v[42:45]
	v_exp_f32_e32 v136, v136
	v_mfma_f32_16x16x32_bf16 v[46:49], v[222:225], v[102:105], v[46:49]
	v_exp_f32_e32 v137, v137
	s_waitcnt lgkmcnt(6)
	v_mfma_f32_16x16x32_bf16 v[50:53], v[202:205], v[98:101], v[50:53]
	v_exp_f32_e32 v138, v138
	ds_read_b128 v[178:181], v234 offset:0
	v_mfma_f32_16x16x32_bf16 v[54:57], v[202:205], v[102:105], v[54:57]
	v_exp_f32_e32 v139, v139
	s_waitcnt lgkmcnt(5)
	v_mfma_f32_16x16x32_bf16 v[58:61], v[206:209], v[98:101], v[58:61]
	v_exp_f32_e32 v140, v140
	ds_read_b128 v[182:185], v234 offset:4096
	v_mfma_f32_16x16x32_bf16 v[62:65], v[206:209], v[102:105], v[62:65]
	v_exp_f32_e32 v141, v141
	s_waitcnt lgkmcnt(4)
	v_mfma_f32_16x16x32_bf16 v[66:69], v[210:213], v[98:101], v[66:69]
	v_exp_f32_e32 v142, v142
	ds_read_b128 v[186:189], v234 offset:8192
	v_mfma_f32_16x16x32_bf16 v[70:73], v[210:213], v[102:105], v[70:73]
	v_exp_f32_e32 v143, v143
	s_waitcnt lgkmcnt(3)
	v_mfma_f32_16x16x32_bf16 v[74:77], v[214:217], v[98:101], v[74:77]
	v_exp_f32_e32 v144, v144
	ds_read_b128 v[190:193], v234 offset:12288
	v_mfma_f32_16x16x32_bf16 v[78:81], v[214:217], v[102:105], v[78:81]
	v_exp_f32_e32 v145, v145
	s_waitcnt vmcnt(4)
	s_barrier
; __device__ __forceinline__ void finishSM(f32x16& p0, f32x16& p1, float& l_reg, bf16x8& pa0, bf16x8& pa1, bf16x8& pa2, bf16x8& pa3) {
;   for (int r = 0; r < 16; ++r) p1[r] = __builtin_amdgcn_exp2f(p1[r]);
;   float ps = 0; for (int r = 0; r < 16; ++r) ps += p0[r]; for (int r = 0; r < 16; ++r) ps += p1[r];
;   { auto rr = __builtin_amdgcn_permlane32_swap(__float_as_uint(ps), __float_as_uint(ps), false, false);
;     ps = __uint_as_float(rr[0]) + __uint_as_float(rr[1]); }
;   l_reg += ps;
;     ...
;   PK4(p0, 0, pa0); PK4(p0, 8, pa1); PK4(p1, 0, pa2); PK4(p1, 8, pa3);
;     ...
; }
; __device__ __forceinline__ void qkt(f32x16& p0, f32x16& p1, const bf16* Ks, const bf16x8* qr, int r32, int hi, const f32x16& negm) {
; #pragma unroll
;   for (int d0 = 0; d0 < 8; ++d0) { int cb = (d0 * 16 + hi * 8) * 2;
;     bf16x8 b0 = *reinterpret_cast<const bf16x8*>((const char*)Ks + KSWZ(r32, cb));
;     bf16x8 b1 = *reinterpret_cast<const bf16x8*>((const char*)Ks + KSWZ(32 + r32, cb));
;     if (d0 == 0) { p0 = __builtin_amdgcn_mfma_f32_32x32x16_bf16(b0, qr[0], negm, 0, 0, 0); p1 = __builtin_amdgcn_mfma_f32_32x32x16_bf16(b1, qr[0], negm, 0, 0, 0); }
;     else { p0 = __builtin_amdgcn_mfma_f32_32x32x16_bf16(b0, qr[d0], p0, 0, 0, 0); p1 = __builtin_amdgcn_mfma_f32_32x32x16_bf16(b1, qr[d0], p1, 0, 0, 0); } }
; }
	s_waitcnt lgkmcnt(3)
	v_mfma_f32_16x16x32_bf16 v[82:85], v[178:181], v[146:149], v[2:5]
	v_add_f32_e32 v250, v114, v250
	s_add_u32 s98, s98, 0x8000
	s_addc_u32 s99, s99, 0
	s_add_u32 s100, s100, 0x8000
	s_addc_u32 s101, s101, 0
	v_mfma_f32_16x16x32_bf16 v[86:89], v[178:181], v[162:165], v[2:5]
	ds_read_b128 v[178:181], v235 offset:0
	v_add_f32_e32 v250, v115, v250
	v_add_f32_e32 v250, v116, v250
	s_waitcnt lgkmcnt(3)
	v_mfma_f32_16x16x32_bf16 v[90:93], v[182:185], v[146:149], v[2:5]
	v_add_f32_e32 v250, v117, v250
	v_mfma_f32_16x16x32_bf16 v[94:97], v[182:185], v[162:165], v[2:5]
	ds_read_b128 v[182:185], v235 offset:4096
	v_add_f32_e32 v250, v122, v250
	v_add_f32_e32 v250, v123, v250
	s_waitcnt lgkmcnt(3)
	v_mfma_f32_16x16x32_bf16 v[98:101], v[186:189], v[146:149], v[2:5]
	v_add_f32_e32 v250, v124, v250
	v_mfma_f32_16x16x32_bf16 v[102:105], v[186:189], v[162:165], v[2:5]
	ds_read_b128 v[186:189], v235 offset:8192
	v_add_f32_e32 v250, v125, v250
	v_cvt_pk_bf16_f32 v114, v114, v115
	s_waitcnt lgkmcnt(3)
	v_mfma_f32_16x16x32_bf16 v[106:109], v[190:193], v[146:149], v[2:5]
	v_cvt_pk_bf16_f32 v115, v116, v117
	s_add_u32 m0, s79, 49152
	s_nop 0
	global_load_lds_dwordx4 v246, s[98:99]
	v_mfma_f32_16x16x32_bf16 v[110:113], v[190:193], v[162:165], v[2:5]
	ds_read_b128 v[190:193], v235 offset:12288
	v_cvt_pk_bf16_f32 v116, v122, v123
	v_cvt_pk_bf16_f32 v117, v124, v125
	s_waitcnt lgkmcnt(3)
	v_mfma_f32_16x16x32_bf16 v[82:85], v[178:181], v[150:153], v[82:85]
	v_add_f32_e32 v251, v118, v251
	v_mfma_f32_16x16x32_bf16 v[86:89], v[178:181], v[166:169], v[86:89]
	ds_read_b128 v[178:181], v236 offset:0
	v_add_f32_e32 v251, v119, v251
	v_add_f32_e32 v251, v120, v251
	s_waitcnt lgkmcnt(3)
	v_mfma_f32_16x16x32_bf16 v[90:93], v[182:185], v[150:153], v[90:93]
	v_add_f32_e32 v251, v121, v251
	v_mfma_f32_16x16x32_bf16 v[94:97], v[182:185], v[166:169], v[94:97]
	ds_read_b128 v[182:185], v236 offset:4096
	v_add_f32_e32 v251, v126, v251
	v_add_f32_e32 v251, v127, v251
	s_waitcnt lgkmcnt(3)
	v_mfma_f32_16x16x32_bf16 v[98:101], v[186:189], v[150:153], v[98:101]
	v_add_f32_e32 v251, v128, v251
	v_mfma_f32_16x16x32_bf16 v[102:105], v[186:189], v[166:169], v[102:105]
	ds_read_b128 v[186:189], v236 offset:8192
	v_add_f32_e32 v251, v129, v251
	v_cvt_pk_bf16_f32 v118, v118, v119
	s_waitcnt lgkmcnt(3)
	v_mfma_f32_16x16x32_bf16 v[106:109], v[190:193], v[150:153], v[106:109]
	v_cvt_pk_bf16_f32 v119, v120, v121
	s_add_u32 m0, s79, 50176
	s_nop 0
	global_load_lds_dwordx4 v247, s[98:99]
	v_mfma_f32_16x16x32_bf16 v[110:113], v[190:193], v[166:169], v[110:113]
	ds_read_b128 v[190:193], v236 offset:12288
	v_cvt_pk_bf16_f32 v120, v126, v127
	v_cvt_pk_bf16_f32 v121, v128, v129
	s_waitcnt lgkmcnt(3)
	v_mfma_f32_16x16x32_bf16 v[82:85], v[178:181], v[154:157], v[82:85]
	v_add_f32_e32 v250, v130, v250
	v_mfma_f32_16x16x32_bf16 v[86:89], v[178:181], v[170:173], v[86:89]
	ds_read_b128 v[178:181], v237 offset:0
	v_add_f32_e32 v250, v131, v250
	v_add_f32_e32 v250, v132, v250
	s_waitcnt lgkmcnt(3)
	v_mfma_f32_16x16x32_bf16 v[90:93], v[182:185], v[154:157], v[90:93]
	v_add_f32_e32 v250, v133, v250
	v_mfma_f32_16x16x32_bf16 v[94:97], v[182:185], v[170:173], v[94:97]
	ds_read_b128 v[182:185], v237 offset:4096
	v_add_f32_e32 v250, v138, v250
	v_add_f32_e32 v250, v139, v250
	s_waitcnt lgkmcnt(3)
	v_mfma_f32_16x16x32_bf16 v[98:101], v[186:189], v[154:157], v[98:101]
	v_add_f32_e32 v250, v140, v250
	ds_read_b64_tr_b16 v[202:203], v238 offset:49152
	ds_read_b64_tr_b16 v[204:205], v238 offset:53248
	v_mfma_f32_16x16x32_bf16 v[102:105], v[186:189], v[170:173], v[102:105]
	ds_read_b128 v[186:189], v237 offset:8192
	v_add_f32_e32 v250, v141, v250
	v_cvt_pk_bf16_f32 v130, v130, v131
	s_waitcnt lgkmcnt(5)
	v_mfma_f32_16x16x32_bf16 v[106:109], v[190:193], v[154:157], v[106:109]
	v_cvt_pk_bf16_f32 v131, v132, v133
	s_add_u32 m0, s80, 32768
	s_nop 0
	global_load_lds_dwordx4 v248, s[100:101]
	ds_read_b64_tr_b16 v[206:207], v239 offset:49152
	ds_read_b64_tr_b16 v[208:209], v239 offset:53248
	v_mfma_f32_16x16x32_bf16 v[110:113], v[190:193], v[170:173], v[110:113]
	ds_read_b128 v[190:193], v237 offset:12288
	v_cvt_pk_bf16_f32 v132, v138, v139
	v_cvt_pk_bf16_f32 v133, v140, v141
	s_waitcnt lgkmcnt(7)
	v_mfma_f32_16x16x32_bf16 v[82:85], v[178:181], v[158:161], v[82:85]
	v_add_f32_e32 v251, v134, v251
	ds_read_b64_tr_b16 v[210:211], v240 offset:49152
	ds_read_b64_tr_b16 v[212:213], v240 offset:53248
	v_mfma_f32_16x16x32_bf16 v[86:89], v[178:181], v[174:177], v[86:89]
	v_add_f32_e32 v251, v135, v251
	v_add_f32_e32 v251, v136, v251
	s_waitcnt lgkmcnt(8)
	v_mfma_f32_16x16x32_bf16 v[90:93], v[182:185], v[158:161], v[90:93]
	v_add_f32_e32 v251, v137, v251
	ds_read_b64_tr_b16 v[214:215], v241 offset:49152
	ds_read_b64_tr_b16 v[216:217], v241 offset:53248
	v_mfma_f32_16x16x32_bf16 v[94:97], v[182:185], v[174:177], v[94:97]
	v_add_f32_e32 v251, v142, v251
	v_add_f32_e32 v251, v143, v251
	s_waitcnt lgkmcnt(7)
	v_mfma_f32_16x16x32_bf16 v[98:101], v[186:189], v[158:161], v[98:101]
	v_add_f32_e32 v251, v144, v251
	ds_read_b64_tr_b16 v[218:219], v242 offset:49152
	ds_read_b64_tr_b16 v[220:221], v242 offset:53248
	v_mfma_f32_16x16x32_bf16 v[102:105], v[186:189], v[174:177], v[102:105]
	v_add_f32_e32 v251, v145, v251
	v_cvt_pk_bf16_f32 v134, v134, v135
	s_waitcnt lgkmcnt(6)
; #define SBAR() __builtin_amdgcn_sched_barrier(0)
; #define SLOAD(i, k0) do { sr_[i].vs0 = St::ld8(&Vh[(long)((k0) + sr) * LDK + sc]); sr_[i].vs1 = St::ld8(&Vh[(long)((k0) + 32 + sr) * LDK + sc]); \
;     sr_[i].ks0 = St::ld8(&Kh[(long)((k0) + sr) * LDK + sc]); sr_[i].ks1 = St::ld8(&Kh[(long)((k0) + 32 + sr) * LDK + sc]); } while (0)
; #define SWAIT() do { if constexpr (SDEPTH == 2) asm volatile("s_waitcnt vmcnt(4)" ::: "memory"); else asm volatile("s_waitcnt vmcnt(0)" ::: "memory"); } while (0)
; template <int D0> __device__ __forceinline__ void pv_one(f32x16& od, int vb, bf16x8 pa0, bf16x8 pa1, bf16x8 pa2, bf16x8 pa3) {
;   const s16x4 l0 = tr_read<v_rd_off(D0, 0, 0)>(vb), h0 = tr_read<v_rd_off(D0, 0, 1)>(vb), l1 = tr_read<v_rd_off(D0, 1, 0)>(vb), h1 = tr_read<v_rd_off(D0, 1, 1)>(vb);
;   const s16x4 l2 = tr_read<v_rd_off(D0, 2, 0)>(vb), h2 = tr_read<v_rd_off(D0, 2, 1)>(vb), l3 = tr_read<v_rd_off(D0, 3, 0)>(vb), h3 = tr_read<v_rd_off(D0, 3, 1)>(vb);
;   asm volatile("s_waitcnt lgkmcnt(0)" ::: "memory"); SBAR();
;     ...
;   od = __builtin_amdgcn_mfma_f32_32x32x16_bf16(pa0, PK(l0, h0), od, 0, 0, 0);
;   od = __builtin_amdgcn_mfma_f32_32x32x16_bf16(pa1, PK(l1, h1), od, 0, 0, 0);
;   od = __builtin_amdgcn_mfma_f32_32x32x16_bf16(pa2, PK(l2, h2), od, 0, 0, 0);
;   od = __builtin_amdgcn_mfma_f32_32x32x16_bf16(pa3, PK(l3, h3), od, 0, 0, 0);
;     ...
; }
; __device__ __forceinline__ void pv_d0(f32x16* o, int vb, bf16x8 pa0, bf16x8 pa1, bf16x8 pa2, bf16x8 pa3) {
;   pv_one<0>(o[0], vb, pa0, pa1, pa2, pa3); pv_one<1>(o[1], vb, pa0, pa1, pa2, pa3); pv_one<2>(o[2], vb, pa0, pa1, pa2, pa3); pv_one<3>(o[3], vb, pa0, pa1, pa2, pa3);
; template <typename TQ> ...
;     ...
;   for (int j = 1; j + 1 < NT; j += 2) {
;     SBAR(); SLOAD(SO, (j + SDEPTH) * KVBLK); SBAR();
;     qkt(pB0, pB1, (bf16*)((char*)K_lds + SHM_K), qr, r32, hi, negm);
;     finishSM(pA0, pA1, l_reg, pa0, pa1, pa2, pa3); SBAR();
;     pv_d0(o, vb0, pa0, pa1, pa2, pa3); partialSM(pB0, pB1, mC);
;     __syncthreads(); SWAIT(); SWRITE(0, SE);
;     __syncthreads();
;     SBAR(); if (SDEPTH == 1 || j + 3 < NT) SLOAD(SE, (j + 1 + SDEPTH) * KVBLK); SBAR();
;     qkt(pA0, pA1, K_lds, qr, r32, hi, negm);
;     finishSM(pB0, pB1, l_reg, pa0, pa1, pa2, pa3); SBAR();
;     pv_d0(o, vb0 + (int)SHM_V, pa0, pa1, pa2, pa3); partialSM(pA0, pA1, mC);
;     __syncthreads(); SWAIT(); SWRITE(1, SO);
;     __syncthreads();
;   }
	v_mfma_f32_16x16x32_bf16 v[106:109], v[190:193], v[158:161], v[106:109]
	v_cvt_pk_bf16_f32 v135, v136, v137
	s_add_u32 m0, s80, 33792
	s_nop 0
	global_load_lds_dwordx4 v249, s[100:101]
	ds_read_b64_tr_b16 v[222:223], v243 offset:49152
	ds_read_b64_tr_b16 v[224:225], v243 offset:53248
	v_mfma_f32_16x16x32_bf16 v[110:113], v[190:193], v[174:177], v[110:113]
	v_cvt_pk_bf16_f32 v136, v142, v143
	v_cvt_pk_bf16_f32 v137, v144, v145
	v_mfma_f32_16x16x32_bf16 v[18:21], v[202:205], v[114:117], v[18:21]
	v_exp_f32_e32 v82, v82
	v_mfma_f32_16x16x32_bf16 v[22:25], v[202:205], v[118:121], v[22:25]
	ds_read_b64_tr_b16 v[202:203], v244 offset:49152
	ds_read_b64_tr_b16 v[204:205], v244 offset:53248
	v_exp_f32_e32 v83, v83
	v_mfma_f32_16x16x32_bf16 v[26:29], v[206:209], v[114:117], v[26:29]
	v_exp_f32_e32 v84, v84
	v_mfma_f32_16x16x32_bf16 v[30:33], v[206:209], v[118:121], v[30:33]
	ds_read_b64_tr_b16 v[206:207], v245 offset:49152
	ds_read_b64_tr_b16 v[208:209], v245 offset:53248
	v_exp_f32_e32 v85, v85
	s_waitcnt lgkmcnt(10)
	v_mfma_f32_16x16x32_bf16 v[34:37], v[210:213], v[114:117], v[34:37]
	v_exp_f32_e32 v86, v86
	v_mfma_f32_16x16x32_bf16 v[38:41], v[210:213], v[118:121], v[38:41]
	ds_read_b64_tr_b16 v[210:211], v238 offset:57344
	ds_read_b64_tr_b16 v[212:213], v238 offset:61440
	v_exp_f32_e32 v87, v87
	s_waitcnt lgkmcnt(10)
	v_mfma_f32_16x16x32_bf16 v[42:45], v[214:217], v[114:117], v[42:45]
	v_exp_f32_e32 v88, v88
	v_mfma_f32_16x16x32_bf16 v[46:49], v[214:217], v[118:121], v[46:49]
	ds_read_b64_tr_b16 v[214:215], v239 offset:57344
	ds_read_b64_tr_b16 v[216:217], v239 offset:61440
	v_exp_f32_e32 v89, v89
	s_waitcnt lgkmcnt(10)
	v_mfma_f32_16x16x32_bf16 v[50:53], v[218:221], v[114:117], v[50:53]
	v_exp_f32_e32 v90, v90
	v_mfma_f32_16x16x32_bf16 v[54:57], v[218:221], v[118:121], v[54:57]
	ds_read_b64_tr_b16 v[218:219], v240 offset:57344
	ds_read_b64_tr_b16 v[220:221], v240 offset:61440
	v_exp_f32_e32 v91, v91
	s_waitcnt lgkmcnt(10)
	v_mfma_f32_16x16x32_bf16 v[58:61], v[222:225], v[114:117], v[58:61]
	v_exp_f32_e32 v92, v92
	v_mfma_f32_16x16x32_bf16 v[62:65], v[222:225], v[118:121], v[62:65]
	ds_read_b64_tr_b16 v[222:223], v241 offset:57344
	ds_read_b64_tr_b16 v[224:225], v241 offset:61440
	v_exp_f32_e32 v93, v93
	s_waitcnt lgkmcnt(10)
	v_mfma_f32_16x16x32_bf16 v[66:69], v[202:205], v[114:117], v[66:69]
	v_exp_f32_e32 v94, v94
	v_mfma_f32_16x16x32_bf16 v[70:73], v[202:205], v[118:121], v[70:73]
	ds_read_b64_tr_b16 v[202:203], v242 offset:57344
	ds_read_b64_tr_b16 v[204:205], v242 offset:61440
	v_exp_f32_e32 v95, v95
	s_waitcnt lgkmcnt(10)
	v_mfma_f32_16x16x32_bf16 v[74:77], v[206:209], v[114:117], v[74:77]
	v_exp_f32_e32 v96, v96
	v_mfma_f32_16x16x32_bf16 v[78:81], v[206:209], v[118:121], v[78:81]
	ds_read_b64_tr_b16 v[206:207], v243 offset:57344
	ds_read_b64_tr_b16 v[208:209], v243 offset:61440
	v_exp_f32_e32 v97, v97
	s_waitcnt lgkmcnt(10)
	v_mfma_f32_16x16x32_bf16 v[18:21], v[210:213], v[130:133], v[18:21]
	v_exp_f32_e32 v98, v98
	v_mfma_f32_16x16x32_bf16 v[22:25], v[210:213], v[134:137], v[22:25]
	ds_read_b64_tr_b16 v[210:211], v244 offset:57344
	ds_read_b64_tr_b16 v[212:213], v244 offset:61440
	v_exp_f32_e32 v99, v99
	s_waitcnt lgkmcnt(10)
	v_mfma_f32_16x16x32_bf16 v[26:29], v[214:217], v[130:133], v[26:29]
	v_exp_f32_e32 v100, v100
	v_mfma_f32_16x16x32_bf16 v[30:33], v[214:217], v[134:137], v[30:33]
	ds_read_b64_tr_b16 v[214:215], v245 offset:57344
	ds_read_b64_tr_b16 v[216:217], v245 offset:61440
	v_exp_f32_e32 v101, v101
	s_waitcnt lgkmcnt(10)
	v_mfma_f32_16x16x32_bf16 v[34:37], v[218:221], v[130:133], v[34:37]
	v_exp_f32_e32 v102, v102
	v_mfma_f32_16x16x32_bf16 v[38:41], v[218:221], v[134:137], v[38:41]
	v_exp_f32_e32 v103, v103
	s_waitcnt lgkmcnt(8)
	v_mfma_f32_16x16x32_bf16 v[42:45], v[222:225], v[130:133], v[42:45]
	v_exp_f32_e32 v104, v104
	v_mfma_f32_16x16x32_bf16 v[46:49], v[222:225], v[134:137], v[46:49]
	v_exp_f32_e32 v105, v105
	s_waitcnt lgkmcnt(6)
	v_mfma_f32_16x16x32_bf16 v[50:53], v[202:205], v[130:133], v[50:53]
	v_exp_f32_e32 v106, v106
	ds_read_b128 v[178:181], v234 offset:16384
	v_mfma_f32_16x16x32_bf16 v[54:57], v[202:205], v[134:137], v[54:57]
	v_exp_f32_e32 v107, v107
	s_waitcnt lgkmcnt(5)
	v_mfma_f32_16x16x32_bf16 v[58:61], v[206:209], v[130:133], v[58:61]
	v_exp_f32_e32 v108, v108
	ds_read_b128 v[182:185], v234 offset:20480
	v_mfma_f32_16x16x32_bf16 v[62:65], v[206:209], v[134:137], v[62:65]
	v_exp_f32_e32 v109, v109
	s_waitcnt lgkmcnt(4)
	v_mfma_f32_16x16x32_bf16 v[66:69], v[210:213], v[130:133], v[66:69]
	v_exp_f32_e32 v110, v110
	ds_read_b128 v[186:189], v234 offset:24576
	v_mfma_f32_16x16x32_bf16 v[70:73], v[210:213], v[134:137], v[70:73]
	v_exp_f32_e32 v111, v111
	s_waitcnt lgkmcnt(3)
	v_mfma_f32_16x16x32_bf16 v[74:77], v[214:217], v[130:133], v[74:77]
	v_exp_f32_e32 v112, v112
	ds_read_b128 v[190:193], v234 offset:28672
	v_mfma_f32_16x16x32_bf16 v[78:81], v[214:217], v[134:137], v[78:81]
	v_exp_f32_e32 v113, v113
	s_waitcnt vmcnt(4)
	s_add_i32 s15, s15, 1
	s_cmp_lt_u32 s15, 32
	s_cbranch_scc1 .Lattn_loop
	s_barrier
; __device__ __forceinline__ void finishSM(f32x16& p0, f32x16& p1, float& l_reg, bf16x8& pa0, bf16x8& pa1, bf16x8& pa2, bf16x8& pa3) {
;   for (int r = 0; r < 16; ++r) p1[r] = __builtin_amdgcn_exp2f(p1[r]);
;   float ps = 0; for (int r = 0; r < 16; ++r) ps += p0[r]; for (int r = 0; r < 16; ++r) ps += p1[r];
;   { auto rr = __builtin_amdgcn_permlane32_swap(__float_as_uint(ps), __float_as_uint(ps), false, false);
;     ps = __uint_as_float(rr[0]) + __uint_as_float(rr[1]); }
;   l_reg += ps;
;     ...
;   PK4(p0, 0, pa0); PK4(p0, 8, pa1); PK4(p1, 0, pa2); PK4(p1, 8, pa3);
;     ...
; }
; __device__ __forceinline__ void qkt(f32x16& p0, f32x16& p1, const bf16* Ks, const bf16x8* qr, int r32, int hi, const f32x16& negm) {
; #pragma unroll
;   for (int d0 = 0; d0 < 8; ++d0) { int cb = (d0 * 16 + hi * 8) * 2;
;     bf16x8 b0 = *reinterpret_cast<const bf16x8*>((const char*)Ks + KSWZ(r32, cb));
;     bf16x8 b1 = *reinterpret_cast<const bf16x8*>((const char*)Ks + KSWZ(32 + r32, cb));
;     if (d0 == 0) { p0 = __builtin_amdgcn_mfma_f32_32x32x16_bf16(b0, qr[0], negm, 0, 0, 0); p1 = __builtin_amdgcn_mfma_f32_32x32x16_bf16(b1, qr[0], negm, 0, 0, 0); }
;     else { p0 = __builtin_amdgcn_mfma_f32_32x32x16_bf16(b0, qr[d0], p0, 0, 0, 0); p1 = __builtin_amdgcn_mfma_f32_32x32x16_bf16(b1, qr[d0], p1, 0, 0, 0); } }
; }
	s_waitcnt lgkmcnt(3)
	v_mfma_f32_16x16x32_bf16 v[114:117], v[178:181], v[146:149], v[2:5]
	v_add_f32_e32 v250, v82, v250
	s_add_u32 s98, s98, 0x8000
	s_addc_u32 s99, s99, 0
	s_add_u32 s100, s100, 0x8000
	s_addc_u32 s101, s101, 0
	v_mfma_f32_16x16x32_bf16 v[118:121], v[178:181], v[162:165], v[2:5]
	ds_read_b128 v[178:181], v235 offset:16384
	v_add_f32_e32 v250, v83, v250
	v_add_f32_e32 v250, v84, v250
	s_waitcnt lgkmcnt(3)
	v_mfma_f32_16x16x32_bf16 v[122:125], v[182:185], v[146:149], v[2:5]
	v_add_f32_e32 v250, v85, v250
	v_mfma_f32_16x16x32_bf16 v[126:129], v[182:185], v[162:165], v[2:5]
	ds_read_b128 v[182:185], v235 offset:20480
	v_add_f32_e32 v250, v90, v250
	v_add_f32_e32 v250, v91, v250
	s_waitcnt lgkmcnt(3)
	v_mfma_f32_16x16x32_bf16 v[130:133], v[186:189], v[146:149], v[2:5]
	v_add_f32_e32 v250, v92, v250
	v_mfma_f32_16x16x32_bf16 v[134:137], v[186:189], v[162:165], v[2:5]
	ds_read_b128 v[186:189], v235 offset:24576
	v_add_f32_e32 v250, v93, v250
	v_cvt_pk_bf16_f32 v82, v82, v83
	s_waitcnt lgkmcnt(3)
	v_mfma_f32_16x16x32_bf16 v[138:141], v[190:193], v[146:149], v[2:5]
	v_cvt_pk_bf16_f32 v83, v84, v85
	s_add_u32 m0, s80, 49152
	s_nop 0
	global_load_lds_dwordx4 v248, s[100:101]
	v_mfma_f32_16x16x32_bf16 v[142:145], v[190:193], v[162:165], v[2:5]
	ds_read_b128 v[190:193], v235 offset:28672
	v_cvt_pk_bf16_f32 v84, v90, v91
	v_cvt_pk_bf16_f32 v85, v92, v93
	s_waitcnt lgkmcnt(3)
	v_mfma_f32_16x16x32_bf16 v[114:117], v[178:181], v[150:153], v[114:117]
	v_add_f32_e32 v251, v86, v251
	v_mfma_f32_16x16x32_bf16 v[118:121], v[178:181], v[166:169], v[118:121]
	ds_read_b128 v[178:181], v236 offset:16384
	v_add_f32_e32 v251, v87, v251
	v_add_f32_e32 v251, v88, v251
	s_waitcnt lgkmcnt(3)
	v_mfma_f32_16x16x32_bf16 v[122:125], v[182:185], v[150:153], v[122:125]
	v_add_f32_e32 v251, v89, v251
	v_mfma_f32_16x16x32_bf16 v[126:129], v[182:185], v[166:169], v[126:129]
	ds_read_b128 v[182:185], v236 offset:20480
	v_add_f32_e32 v251, v94, v251
	v_add_f32_e32 v251, v95, v251
	s_waitcnt lgkmcnt(3)
	v_mfma_f32_16x16x32_bf16 v[130:133], v[186:189], v[150:153], v[130:133]
	v_add_f32_e32 v251, v96, v251
	v_mfma_f32_16x16x32_bf16 v[134:137], v[186:189], v[166:169], v[134:137]
	ds_read_b128 v[186:189], v236 offset:24576
	v_add_f32_e32 v251, v97, v251
	v_cvt_pk_bf16_f32 v86, v86, v87
	s_waitcnt lgkmcnt(3)
	v_mfma_f32_16x16x32_bf16 v[138:141], v[190:193], v[150:153], v[138:141]
	v_cvt_pk_bf16_f32 v87, v88, v89
	s_add_u32 m0, s80, 50176
	s_nop 0
	global_load_lds_dwordx4 v249, s[100:101]
	v_mfma_f32_16x16x32_bf16 v[142:145], v[190:193], v[166:169], v[142:145]
	ds_read_b128 v[190:193], v236 offset:28672
	v_cvt_pk_bf16_f32 v88, v94, v95
	v_cvt_pk_bf16_f32 v89, v96, v97
	s_waitcnt lgkmcnt(3)
	v_mfma_f32_16x16x32_bf16 v[114:117], v[178:181], v[154:157], v[114:117]
	v_add_f32_e32 v250, v98, v250
	v_mfma_f32_16x16x32_bf16 v[118:121], v[178:181], v[170:173], v[118:121]
	ds_read_b128 v[178:181], v237 offset:16384
	v_add_f32_e32 v250, v99, v250
	v_add_f32_e32 v250, v100, v250
	s_waitcnt lgkmcnt(3)
	v_mfma_f32_16x16x32_bf16 v[122:125], v[182:185], v[154:157], v[122:125]
	v_add_f32_e32 v250, v101, v250
	v_mfma_f32_16x16x32_bf16 v[126:129], v[182:185], v[170:173], v[126:129]
	ds_read_b128 v[182:185], v237 offset:20480
	v_add_f32_e32 v250, v106, v250
	v_add_f32_e32 v250, v107, v250
	s_waitcnt lgkmcnt(3)
	v_mfma_f32_16x16x32_bf16 v[130:133], v[186:189], v[154:157], v[130:133]
	v_add_f32_e32 v250, v108, v250
	ds_read_b64_tr_b16 v[202:203], v238 offset:0
	ds_read_b64_tr_b16 v[204:205], v238 offset:4096
	v_mfma_f32_16x16x32_bf16 v[134:137], v[186:189], v[170:173], v[134:137]
	ds_read_b128 v[186:189], v237 offset:24576
	v_add_f32_e32 v250, v109, v250
	v_cvt_pk_bf16_f32 v98, v98, v99
	s_waitcnt lgkmcnt(5)
	v_mfma_f32_16x16x32_bf16 v[138:141], v[190:193], v[154:157], v[138:141]
	v_cvt_pk_bf16_f32 v99, v100, v101
	ds_read_b64_tr_b16 v[206:207], v239 offset:0
	ds_read_b64_tr_b16 v[208:209], v239 offset:4096
	v_mfma_f32_16x16x32_bf16 v[142:145], v[190:193], v[170:173], v[142:145]
	ds_read_b128 v[190:193], v237 offset:28672
	v_cvt_pk_bf16_f32 v100, v106, v107
	v_cvt_pk_bf16_f32 v101, v108, v109
	s_waitcnt lgkmcnt(7)
	v_mfma_f32_16x16x32_bf16 v[114:117], v[178:181], v[158:161], v[114:117]
	v_add_f32_e32 v251, v102, v251
	ds_read_b64_tr_b16 v[210:211], v240 offset:0
	ds_read_b64_tr_b16 v[212:213], v240 offset:4096
	v_mfma_f32_16x16x32_bf16 v[118:121], v[178:181], v[174:177], v[118:121]
	v_add_f32_e32 v251, v103, v251
	v_add_f32_e32 v251, v104, v251
	s_waitcnt lgkmcnt(8)
	v_mfma_f32_16x16x32_bf16 v[122:125], v[182:185], v[158:161], v[122:125]
	v_add_f32_e32 v251, v105, v251
	ds_read_b64_tr_b16 v[214:215], v241 offset:0
	ds_read_b64_tr_b16 v[216:217], v241 offset:4096
	v_mfma_f32_16x16x32_bf16 v[126:129], v[182:185], v[174:177], v[126:129]
	v_add_f32_e32 v251, v110, v251
	v_add_f32_e32 v251, v111, v251
	s_waitcnt lgkmcnt(7)
	v_mfma_f32_16x16x32_bf16 v[130:133], v[186:189], v[158:161], v[130:133]
	v_add_f32_e32 v251, v112, v251
	ds_read_b64_tr_b16 v[218:219], v242 offset:0
	ds_read_b64_tr_b16 v[220:221], v242 offset:4096
	v_mfma_f32_16x16x32_bf16 v[134:137], v[186:189], v[174:177], v[134:137]
	v_add_f32_e32 v251, v113, v251
	v_cvt_pk_bf16_f32 v102, v102, v103
	s_waitcnt lgkmcnt(6)
; #define SBAR() __builtin_amdgcn_sched_barrier(0)
; __device__ __forceinline__ void partialSM(f32x16& p0, f32x16& p1, float mC) {
;   (void)mC; (void)p1;
;   for (int r = 0; r < 16; ++r) p0[r] = __builtin_amdgcn_exp2f(p0[r]);
; }
; template <int D0> __device__ __forceinline__ void pv_one(f32x16& od, int vb, bf16x8 pa0, bf16x8 pa1, bf16x8 pa2, bf16x8 pa3) {
;   const s16x4 l0 = tr_read<v_rd_off(D0, 0, 0)>(vb), h0 = tr_read<v_rd_off(D0, 0, 1)>(vb), l1 = tr_read<v_rd_off(D0, 1, 0)>(vb), h1 = tr_read<v_rd_off(D0, 1, 1)>(vb);
;   const s16x4 l2 = tr_read<v_rd_off(D0, 2, 0)>(vb), h2 = tr_read<v_rd_off(D0, 2, 1)>(vb), l3 = tr_read<v_rd_off(D0, 3, 0)>(vb), h3 = tr_read<v_rd_off(D0, 3, 1)>(vb);
;   asm volatile("s_waitcnt lgkmcnt(0)" ::: "memory"); SBAR();
;     ...
;   od = __builtin_amdgcn_mfma_f32_32x32x16_bf16(pa0, PK(l0, h0), od, 0, 0, 0);
;   od = __builtin_amdgcn_mfma_f32_32x32x16_bf16(pa1, PK(l1, h1), od, 0, 0, 0);
;   od = __builtin_amdgcn_mfma_f32_32x32x16_bf16(pa2, PK(l2, h2), od, 0, 0, 0);
;   od = __builtin_amdgcn_mfma_f32_32x32x16_bf16(pa3, PK(l3, h3), od, 0, 0, 0);
;     ...
; }
; __device__ __forceinline__ void pv_d0(f32x16* o, int vb, bf16x8 pa0, bf16x8 pa1, bf16x8 pa2, bf16x8 pa3) {
;   pv_one<0>(o[0], vb, pa0, pa1, pa2, pa3); pv_one<1>(o[1], vb, pa0, pa1, pa2, pa3); pv_one<2>(o[2], vb, pa0, pa1, pa2, pa3); pv_one<3>(o[3], vb, pa0, pa1, pa2, pa3);
	v_mfma_f32_16x16x32_bf16 v[138:141], v[190:193], v[158:161], v[138:141]
	v_cvt_pk_bf16_f32 v103, v104, v105
	ds_read_b64_tr_b16 v[222:223], v243 offset:0
	ds_read_b64_tr_b16 v[224:225], v243 offset:4096
	v_mfma_f32_16x16x32_bf16 v[142:145], v[190:193], v[174:177], v[142:145]
	v_cvt_pk_bf16_f32 v104, v110, v111
	v_cvt_pk_bf16_f32 v105, v112, v113
	v_mfma_f32_16x16x32_bf16 v[18:21], v[202:205], v[82:85], v[18:21]
	v_exp_f32_e32 v114, v114
	v_mfma_f32_16x16x32_bf16 v[22:25], v[202:205], v[86:89], v[22:25]
	ds_read_b64_tr_b16 v[202:203], v244 offset:0
	ds_read_b64_tr_b16 v[204:205], v244 offset:4096
	v_exp_f32_e32 v115, v115
	v_mfma_f32_16x16x32_bf16 v[26:29], v[206:209], v[82:85], v[26:29]
	v_exp_f32_e32 v116, v116
	v_mfma_f32_16x16x32_bf16 v[30:33], v[206:209], v[86:89], v[30:33]
	ds_read_b64_tr_b16 v[206:207], v245 offset:0
	ds_read_b64_tr_b16 v[208:209], v245 offset:4096
	v_exp_f32_e32 v117, v117
	s_waitcnt lgkmcnt(10)
	v_mfma_f32_16x16x32_bf16 v[34:37], v[210:213], v[82:85], v[34:37]
	v_exp_f32_e32 v118, v118
	v_mfma_f32_16x16x32_bf16 v[38:41], v[210:213], v[86:89], v[38:41]
	ds_read_b64_tr_b16 v[210:211], v238 offset:8192
	ds_read_b64_tr_b16 v[212:213], v238 offset:12288
	v_exp_f32_e32 v119, v119
	s_waitcnt lgkmcnt(10)
	v_mfma_f32_16x16x32_bf16 v[42:45], v[214:217], v[82:85], v[42:45]
	v_exp_f32_e32 v120, v120
	v_mfma_f32_16x16x32_bf16 v[46:49], v[214:217], v[86:89], v[46:49]
	ds_read_b64_tr_b16 v[214:215], v239 offset:8192
	ds_read_b64_tr_b16 v[216:217], v239 offset:12288
	v_exp_f32_e32 v121, v121
	s_waitcnt lgkmcnt(10)
	v_mfma_f32_16x16x32_bf16 v[50:53], v[218:221], v[82:85], v[50:53]
	v_exp_f32_e32 v122, v122
	v_mfma_f32_16x16x32_bf16 v[54:57], v[218:221], v[86:89], v[54:57]
	ds_read_b64_tr_b16 v[218:219], v240 offset:8192
	ds_read_b64_tr_b16 v[220:221], v240 offset:12288
	v_exp_f32_e32 v123, v123
	s_waitcnt lgkmcnt(10)
	v_mfma_f32_16x16x32_bf16 v[58:61], v[222:225], v[82:85], v[58:61]
	v_exp_f32_e32 v124, v124
	v_mfma_f32_16x16x32_bf16 v[62:65], v[222:225], v[86:89], v[62:65]
	ds_read_b64_tr_b16 v[222:223], v241 offset:8192
	ds_read_b64_tr_b16 v[224:225], v241 offset:12288
	v_exp_f32_e32 v125, v125
	s_waitcnt lgkmcnt(10)
	v_mfma_f32_16x16x32_bf16 v[66:69], v[202:205], v[82:85], v[66:69]
	v_exp_f32_e32 v126, v126
	v_mfma_f32_16x16x32_bf16 v[70:73], v[202:205], v[86:89], v[70:73]
	ds_read_b64_tr_b16 v[202:203], v242 offset:8192
	ds_read_b64_tr_b16 v[204:205], v242 offset:12288
	v_exp_f32_e32 v127, v127
	s_waitcnt lgkmcnt(10)
	v_mfma_f32_16x16x32_bf16 v[74:77], v[206:209], v[82:85], v[74:77]
	v_exp_f32_e32 v128, v128
	v_mfma_f32_16x16x32_bf16 v[78:81], v[206:209], v[86:89], v[78:81]
	ds_read_b64_tr_b16 v[206:207], v243 offset:8192
	ds_read_b64_tr_b16 v[208:209], v243 offset:12288
	v_exp_f32_e32 v129, v129
	s_waitcnt lgkmcnt(10)
	v_mfma_f32_16x16x32_bf16 v[18:21], v[210:213], v[98:101], v[18:21]
	v_exp_f32_e32 v130, v130
	v_mfma_f32_16x16x32_bf16 v[22:25], v[210:213], v[102:105], v[22:25]
	ds_read_b64_tr_b16 v[210:211], v244 offset:8192
	ds_read_b64_tr_b16 v[212:213], v244 offset:12288
	v_exp_f32_e32 v131, v131
	s_waitcnt lgkmcnt(10)
	v_mfma_f32_16x16x32_bf16 v[26:29], v[214:217], v[98:101], v[26:29]
	v_exp_f32_e32 v132, v132
	v_mfma_f32_16x16x32_bf16 v[30:33], v[214:217], v[102:105], v[30:33]
	ds_read_b64_tr_b16 v[214:215], v245 offset:8192
	ds_read_b64_tr_b16 v[216:217], v245 offset:12288
	v_exp_f32_e32 v133, v133
	s_waitcnt lgkmcnt(10)
	v_mfma_f32_16x16x32_bf16 v[34:37], v[218:221], v[98:101], v[34:37]
	v_exp_f32_e32 v134, v134
	v_mfma_f32_16x16x32_bf16 v[38:41], v[218:221], v[102:105], v[38:41]
	v_exp_f32_e32 v135, v135
	s_waitcnt lgkmcnt(8)
	v_mfma_f32_16x16x32_bf16 v[42:45], v[222:225], v[98:101], v[42:45]
	v_exp_f32_e32 v136, v136
	v_mfma_f32_16x16x32_bf16 v[46:49], v[222:225], v[102:105], v[46:49]
	v_exp_f32_e32 v137, v137
	s_waitcnt lgkmcnt(6)
	v_mfma_f32_16x16x32_bf16 v[50:53], v[202:205], v[98:101], v[50:53]
	v_exp_f32_e32 v138, v138
	ds_read_b128 v[178:181], v234 offset:32768
	v_mfma_f32_16x16x32_bf16 v[54:57], v[202:205], v[102:105], v[54:57]
	v_exp_f32_e32 v139, v139
	s_waitcnt lgkmcnt(5)
	v_mfma_f32_16x16x32_bf16 v[58:61], v[206:209], v[98:101], v[58:61]
	v_exp_f32_e32 v140, v140
	ds_read_b128 v[182:185], v234 offset:36864
	v_mfma_f32_16x16x32_bf16 v[62:65], v[206:209], v[102:105], v[62:65]
	v_exp_f32_e32 v141, v141
	s_waitcnt lgkmcnt(4)
	v_mfma_f32_16x16x32_bf16 v[66:69], v[210:213], v[98:101], v[66:69]
	v_exp_f32_e32 v142, v142
	ds_read_b128 v[186:189], v234 offset:40960
	v_mfma_f32_16x16x32_bf16 v[70:73], v[210:213], v[102:105], v[70:73]
	v_exp_f32_e32 v143, v143
	s_waitcnt lgkmcnt(3)
	v_mfma_f32_16x16x32_bf16 v[74:77], v[214:217], v[98:101], v[74:77]
	v_exp_f32_e32 v144, v144
	ds_read_b128 v[190:193], v234 offset:45056
	v_mfma_f32_16x16x32_bf16 v[78:81], v[214:217], v[102:105], v[78:81]
	v_exp_f32_e32 v145, v145
	s_waitcnt vmcnt(2)
	s_barrier
; #define SBAR() __builtin_amdgcn_sched_barrier(0)
; __device__ __forceinline__ void qkt(f32x16& p0, f32x16& p1, const bf16* Ks, const bf16x8* qr, int r32, int hi, const f32x16& negm) {
; #pragma unroll
;   for (int d0 = 0; d0 < 8; ++d0) { int cb = (d0 * 16 + hi * 8) * 2;
;     bf16x8 b0 = *reinterpret_cast<const bf16x8*>((const char*)Ks + KSWZ(r32, cb));
;     bf16x8 b1 = *reinterpret_cast<const bf16x8*>((const char*)Ks + KSWZ(32 + r32, cb));
;     if (d0 == 0) { p0 = __builtin_amdgcn_mfma_f32_32x32x16_bf16(b0, qr[0], negm, 0, 0, 0); p1 = __builtin_amdgcn_mfma_f32_32x32x16_bf16(b1, qr[0], negm, 0, 0, 0); }
;     else { p0 = __builtin_amdgcn_mfma_f32_32x32x16_bf16(b0, qr[d0], p0, 0, 0, 0); p1 = __builtin_amdgcn_mfma_f32_32x32x16_bf16(b1, qr[d0], p1, 0, 0, 0); } }
; }
; template <int D0> __device__ __forceinline__ void pv_one(f32x16& od, int vb, bf16x8 pa0, bf16x8 pa1, bf16x8 pa2, bf16x8 pa3) {
;   const s16x4 l0 = tr_read<v_rd_off(D0, 0, 0)>(vb), h0 = tr_read<v_rd_off(D0, 0, 1)>(vb), l1 = tr_read<v_rd_off(D0, 1, 0)>(vb), h1 = tr_read<v_rd_off(D0, 1, 1)>(vb);
;   const s16x4 l2 = tr_read<v_rd_off(D0, 2, 0)>(vb), h2 = tr_read<v_rd_off(D0, 2, 1)>(vb), l3 = tr_read<v_rd_off(D0, 3, 0)>(vb), h3 = tr_read<v_rd_off(D0, 3, 1)>(vb);
;   asm volatile("s_waitcnt lgkmcnt(0)" ::: "memory"); SBAR();
;     ...
;   od = __builtin_amdgcn_mfma_f32_32x32x16_bf16(pa0, PK(l0, h0), od, 0, 0, 0);
;   od = __builtin_amdgcn_mfma_f32_32x32x16_bf16(pa1, PK(l1, h1), od, 0, 0, 0);
;   od = __builtin_amdgcn_mfma_f32_32x32x16_bf16(pa2, PK(l2, h2), od, 0, 0, 0);
;   od = __builtin_amdgcn_mfma_f32_32x32x16_bf16(pa3, PK(l3, h3), od, 0, 0, 0);
;     ...
; }
; __device__ __forceinline__ void pv_d0(f32x16* o, int vb, bf16x8 pa0, bf16x8 pa1, bf16x8 pa2, bf16x8 pa3) {
;   pv_one<0>(o[0], vb, pa0, pa1, pa2, pa3); pv_one<1>(o[1], vb, pa0, pa1, pa2, pa3); pv_one<2>(o[2], vb, pa0, pa1, pa2, pa3); pv_one<3>(o[3], vb, pa0, pa1, pa2, pa3);
	s_waitcnt lgkmcnt(3)
	v_mfma_f32_16x16x32_bf16 v[82:85], v[178:181], v[146:149], v[2:5]
	v_add_f32_e32 v250, v114, v250
	v_mfma_f32_16x16x32_bf16 v[86:89], v[178:181], v[162:165], v[2:5]
	ds_read_b128 v[178:181], v235 offset:32768
	v_add_f32_e32 v250, v115, v250
	v_add_f32_e32 v250, v116, v250
	s_waitcnt lgkmcnt(3)
	v_mfma_f32_16x16x32_bf16 v[90:93], v[182:185], v[146:149], v[2:5]
	v_add_f32_e32 v250, v117, v250
	v_mfma_f32_16x16x32_bf16 v[94:97], v[182:185], v[162:165], v[2:5]
	ds_read_b128 v[182:185], v235 offset:36864
	v_add_f32_e32 v250, v122, v250
	v_add_f32_e32 v250, v123, v250
	s_waitcnt lgkmcnt(3)
	v_mfma_f32_16x16x32_bf16 v[98:101], v[186:189], v[146:149], v[2:5]
	v_add_f32_e32 v250, v124, v250
	v_mfma_f32_16x16x32_bf16 v[102:105], v[186:189], v[162:165], v[2:5]
	ds_read_b128 v[186:189], v235 offset:40960
	v_add_f32_e32 v250, v125, v250
	v_cvt_pk_bf16_f32 v114, v114, v115
	s_waitcnt lgkmcnt(3)
	v_mfma_f32_16x16x32_bf16 v[106:109], v[190:193], v[146:149], v[2:5]
	v_cvt_pk_bf16_f32 v115, v116, v117
	v_mfma_f32_16x16x32_bf16 v[110:113], v[190:193], v[162:165], v[2:5]
	ds_read_b128 v[190:193], v235 offset:45056
	v_cvt_pk_bf16_f32 v116, v122, v123
	v_cvt_pk_bf16_f32 v117, v124, v125
	s_waitcnt lgkmcnt(3)
	v_mfma_f32_16x16x32_bf16 v[82:85], v[178:181], v[150:153], v[82:85]
	v_add_f32_e32 v251, v118, v251
	v_mfma_f32_16x16x32_bf16 v[86:89], v[178:181], v[166:169], v[86:89]
	ds_read_b128 v[178:181], v236 offset:32768
	v_add_f32_e32 v251, v119, v251
	v_add_f32_e32 v251, v120, v251
	s_waitcnt lgkmcnt(3)
	v_mfma_f32_16x16x32_bf16 v[90:93], v[182:185], v[150:153], v[90:93]
	v_add_f32_e32 v251, v121, v251
	v_mfma_f32_16x16x32_bf16 v[94:97], v[182:185], v[166:169], v[94:97]
	ds_read_b128 v[182:185], v236 offset:36864
	v_add_f32_e32 v251, v126, v251
	v_add_f32_e32 v251, v127, v251
	s_waitcnt lgkmcnt(3)
	v_mfma_f32_16x16x32_bf16 v[98:101], v[186:189], v[150:153], v[98:101]
	v_add_f32_e32 v251, v128, v251
	v_mfma_f32_16x16x32_bf16 v[102:105], v[186:189], v[166:169], v[102:105]
	ds_read_b128 v[186:189], v236 offset:40960
	v_add_f32_e32 v251, v129, v251
	v_cvt_pk_bf16_f32 v118, v118, v119
	s_waitcnt lgkmcnt(3)
	v_mfma_f32_16x16x32_bf16 v[106:109], v[190:193], v[150:153], v[106:109]
	v_cvt_pk_bf16_f32 v119, v120, v121
	v_mfma_f32_16x16x32_bf16 v[110:113], v[190:193], v[166:169], v[110:113]
	ds_read_b128 v[190:193], v236 offset:45056
	v_cvt_pk_bf16_f32 v120, v126, v127
	v_cvt_pk_bf16_f32 v121, v128, v129
	s_waitcnt lgkmcnt(3)
	v_mfma_f32_16x16x32_bf16 v[82:85], v[178:181], v[154:157], v[82:85]
	v_add_f32_e32 v250, v130, v250
	v_mfma_f32_16x16x32_bf16 v[86:89], v[178:181], v[170:173], v[86:89]
	ds_read_b128 v[178:181], v237 offset:32768
	v_add_f32_e32 v250, v131, v250
	v_add_f32_e32 v250, v132, v250
	s_waitcnt lgkmcnt(3)
	v_mfma_f32_16x16x32_bf16 v[90:93], v[182:185], v[154:157], v[90:93]
	v_add_f32_e32 v250, v133, v250
	v_mfma_f32_16x16x32_bf16 v[94:97], v[182:185], v[170:173], v[94:97]
	ds_read_b128 v[182:185], v237 offset:36864
	v_add_f32_e32 v250, v138, v250
	v_add_f32_e32 v250, v139, v250
	s_waitcnt lgkmcnt(3)
	v_mfma_f32_16x16x32_bf16 v[98:101], v[186:189], v[154:157], v[98:101]
	v_add_f32_e32 v250, v140, v250
	ds_read_b64_tr_b16 v[202:203], v238 offset:16384
	ds_read_b64_tr_b16 v[204:205], v238 offset:20480
	v_mfma_f32_16x16x32_bf16 v[102:105], v[186:189], v[170:173], v[102:105]
	ds_read_b128 v[186:189], v237 offset:40960
	v_add_f32_e32 v250, v141, v250
	v_cvt_pk_bf16_f32 v130, v130, v131
	s_waitcnt lgkmcnt(5)
	v_mfma_f32_16x16x32_bf16 v[106:109], v[190:193], v[154:157], v[106:109]
	v_cvt_pk_bf16_f32 v131, v132, v133
	ds_read_b64_tr_b16 v[206:207], v239 offset:16384
	ds_read_b64_tr_b16 v[208:209], v239 offset:20480
	v_mfma_f32_16x16x32_bf16 v[110:113], v[190:193], v[170:173], v[110:113]
	ds_read_b128 v[190:193], v237 offset:45056
	v_cvt_pk_bf16_f32 v132, v138, v139
	v_cvt_pk_bf16_f32 v133, v140, v141
	s_waitcnt lgkmcnt(7)
	v_mfma_f32_16x16x32_bf16 v[82:85], v[178:181], v[158:161], v[82:85]
	v_add_f32_e32 v251, v134, v251
	ds_read_b64_tr_b16 v[210:211], v240 offset:16384
	ds_read_b64_tr_b16 v[212:213], v240 offset:20480
	v_mfma_f32_16x16x32_bf16 v[86:89], v[178:181], v[174:177], v[86:89]
	v_add_f32_e32 v251, v135, v251
	v_add_f32_e32 v251, v136, v251
	s_waitcnt lgkmcnt(8)
	v_mfma_f32_16x16x32_bf16 v[90:93], v[182:185], v[158:161], v[90:93]
	v_add_f32_e32 v251, v137, v251
	ds_read_b64_tr_b16 v[214:215], v241 offset:16384
	ds_read_b64_tr_b16 v[216:217], v241 offset:20480
	v_mfma_f32_16x16x32_bf16 v[94:97], v[182:185], v[174:177], v[94:97]
	v_add_f32_e32 v251, v142, v251
	v_add_f32_e32 v251, v143, v251
	s_waitcnt lgkmcnt(7)
	v_mfma_f32_16x16x32_bf16 v[98:101], v[186:189], v[158:161], v[98:101]
	v_add_f32_e32 v251, v144, v251
	ds_read_b64_tr_b16 v[218:219], v242 offset:16384
	ds_read_b64_tr_b16 v[220:221], v242 offset:20480
	v_mfma_f32_16x16x32_bf16 v[102:105], v[186:189], v[174:177], v[102:105]
	v_add_f32_e32 v251, v145, v251
	v_cvt_pk_bf16_f32 v134, v134, v135
	s_waitcnt lgkmcnt(6)
	v_mfma_f32_16x16x32_bf16 v[106:109], v[190:193], v[158:161], v[106:109]
	v_cvt_pk_bf16_f32 v135, v136, v137
	ds_read_b64_tr_b16 v[222:223], v243 offset:16384
	ds_read_b64_tr_b16 v[224:225], v243 offset:20480
	v_mfma_f32_16x16x32_bf16 v[110:113], v[190:193], v[174:177], v[110:113]
	v_cvt_pk_bf16_f32 v136, v142, v143
	v_cvt_pk_bf16_f32 v137, v144, v145
	v_mfma_f32_16x16x32_bf16 v[18:21], v[202:205], v[114:117], v[18:21]
	v_exp_f32_e32 v82, v82
	v_mfma_f32_16x16x32_bf16 v[22:25], v[202:205], v[118:121], v[22:25]
	ds_read_b64_tr_b16 v[202:203], v244 offset:16384
	ds_read_b64_tr_b16 v[204:205], v244 offset:20480
	v_exp_f32_e32 v83, v83
	v_mfma_f32_16x16x32_bf16 v[26:29], v[206:209], v[114:117], v[26:29]
	v_exp_f32_e32 v84, v84
	v_mfma_f32_16x16x32_bf16 v[30:33], v[206:209], v[118:121], v[30:33]
	ds_read_b64_tr_b16 v[206:207], v245 offset:16384
	ds_read_b64_tr_b16 v[208:209], v245 offset:20480
	v_exp_f32_e32 v85, v85
	s_waitcnt lgkmcnt(10)
; #define SBAR() __builtin_amdgcn_sched_barrier(0)
; __device__ __forceinline__ void qkt(f32x16& p0, f32x16& p1, const bf16* Ks, const bf16x8* qr, int r32, int hi, const f32x16& negm) {
; #pragma unroll
;   for (int d0 = 0; d0 < 8; ++d0) { int cb = (d0 * 16 + hi * 8) * 2;
;     bf16x8 b0 = *reinterpret_cast<const bf16x8*>((const char*)Ks + KSWZ(r32, cb));
;     bf16x8 b1 = *reinterpret_cast<const bf16x8*>((const char*)Ks + KSWZ(32 + r32, cb));
;     if (d0 == 0) { p0 = __builtin_amdgcn_mfma_f32_32x32x16_bf16(b0, qr[0], negm, 0, 0, 0); p1 = __builtin_amdgcn_mfma_f32_32x32x16_bf16(b1, qr[0], negm, 0, 0, 0); }
;     else { p0 = __builtin_amdgcn_mfma_f32_32x32x16_bf16(b0, qr[d0], p0, 0, 0, 0); p1 = __builtin_amdgcn_mfma_f32_32x32x16_bf16(b1, qr[d0], p1, 0, 0, 0); } }
; }
; template <int D0> __device__ __forceinline__ void pv_one(f32x16& od, int vb, bf16x8 pa0, bf16x8 pa1, bf16x8 pa2, bf16x8 pa3) {
;   const s16x4 l0 = tr_read<v_rd_off(D0, 0, 0)>(vb), h0 = tr_read<v_rd_off(D0, 0, 1)>(vb), l1 = tr_read<v_rd_off(D0, 1, 0)>(vb), h1 = tr_read<v_rd_off(D0, 1, 1)>(vb);
;   const s16x4 l2 = tr_read<v_rd_off(D0, 2, 0)>(vb), h2 = tr_read<v_rd_off(D0, 2, 1)>(vb), l3 = tr_read<v_rd_off(D0, 3, 0)>(vb), h3 = tr_read<v_rd_off(D0, 3, 1)>(vb);
;   asm volatile("s_waitcnt lgkmcnt(0)" ::: "memory"); SBAR();
;     ...
;   od = __builtin_amdgcn_mfma_f32_32x32x16_bf16(pa0, PK(l0, h0), od, 0, 0, 0);
;   od = __builtin_amdgcn_mfma_f32_32x32x16_bf16(pa1, PK(l1, h1), od, 0, 0, 0);
;   od = __builtin_amdgcn_mfma_f32_32x32x16_bf16(pa2, PK(l2, h2), od, 0, 0, 0);
;   od = __builtin_amdgcn_mfma_f32_32x32x16_bf16(pa3, PK(l3, h3), od, 0, 0, 0);
;     ...
; }
; __device__ __forceinline__ void pv_d0(f32x16* o, int vb, bf16x8 pa0, bf16x8 pa1, bf16x8 pa2, bf16x8 pa3) {
;   pv_one<0>(o[0], vb, pa0, pa1, pa2, pa3); pv_one<1>(o[1], vb, pa0, pa1, pa2, pa3); pv_one<2>(o[2], vb, pa0, pa1, pa2, pa3); pv_one<3>(o[3], vb, pa0, pa1, pa2, pa3);
	v_mfma_f32_16x16x32_bf16 v[34:37], v[210:213], v[114:117], v[34:37]
	v_exp_f32_e32 v86, v86
	v_mfma_f32_16x16x32_bf16 v[38:41], v[210:213], v[118:121], v[38:41]
	ds_read_b64_tr_b16 v[210:211], v238 offset:24576
	ds_read_b64_tr_b16 v[212:213], v238 offset:28672
	v_exp_f32_e32 v87, v87
	s_waitcnt lgkmcnt(10)
	v_mfma_f32_16x16x32_bf16 v[42:45], v[214:217], v[114:117], v[42:45]
	v_exp_f32_e32 v88, v88
	v_mfma_f32_16x16x32_bf16 v[46:49], v[214:217], v[118:121], v[46:49]
	ds_read_b64_tr_b16 v[214:215], v239 offset:24576
	ds_read_b64_tr_b16 v[216:217], v239 offset:28672
	v_exp_f32_e32 v89, v89
	s_waitcnt lgkmcnt(10)
	v_mfma_f32_16x16x32_bf16 v[50:53], v[218:221], v[114:117], v[50:53]
	v_exp_f32_e32 v90, v90
	v_mfma_f32_16x16x32_bf16 v[54:57], v[218:221], v[118:121], v[54:57]
	ds_read_b64_tr_b16 v[218:219], v240 offset:24576
	ds_read_b64_tr_b16 v[220:221], v240 offset:28672
	v_exp_f32_e32 v91, v91
	s_waitcnt lgkmcnt(10)
	v_mfma_f32_16x16x32_bf16 v[58:61], v[222:225], v[114:117], v[58:61]
	v_exp_f32_e32 v92, v92
	v_mfma_f32_16x16x32_bf16 v[62:65], v[222:225], v[118:121], v[62:65]
	ds_read_b64_tr_b16 v[222:223], v241 offset:24576
	ds_read_b64_tr_b16 v[224:225], v241 offset:28672
	v_exp_f32_e32 v93, v93
	s_waitcnt lgkmcnt(10)
	v_mfma_f32_16x16x32_bf16 v[66:69], v[202:205], v[114:117], v[66:69]
	v_exp_f32_e32 v94, v94
	v_mfma_f32_16x16x32_bf16 v[70:73], v[202:205], v[118:121], v[70:73]
	ds_read_b64_tr_b16 v[202:203], v242 offset:24576
	ds_read_b64_tr_b16 v[204:205], v242 offset:28672
	v_exp_f32_e32 v95, v95
	s_waitcnt lgkmcnt(10)
	v_mfma_f32_16x16x32_bf16 v[74:77], v[206:209], v[114:117], v[74:77]
	v_exp_f32_e32 v96, v96
	v_mfma_f32_16x16x32_bf16 v[78:81], v[206:209], v[118:121], v[78:81]
	ds_read_b64_tr_b16 v[206:207], v243 offset:24576
	ds_read_b64_tr_b16 v[208:209], v243 offset:28672
	v_exp_f32_e32 v97, v97
	s_waitcnt lgkmcnt(10)
	v_mfma_f32_16x16x32_bf16 v[18:21], v[210:213], v[130:133], v[18:21]
	v_exp_f32_e32 v98, v98
	v_mfma_f32_16x16x32_bf16 v[22:25], v[210:213], v[134:137], v[22:25]
	ds_read_b64_tr_b16 v[210:211], v244 offset:24576
	ds_read_b64_tr_b16 v[212:213], v244 offset:28672
	v_exp_f32_e32 v99, v99
	s_waitcnt lgkmcnt(10)
	v_mfma_f32_16x16x32_bf16 v[26:29], v[214:217], v[130:133], v[26:29]
	v_exp_f32_e32 v100, v100
	v_mfma_f32_16x16x32_bf16 v[30:33], v[214:217], v[134:137], v[30:33]
	ds_read_b64_tr_b16 v[214:215], v245 offset:24576
	ds_read_b64_tr_b16 v[216:217], v245 offset:28672
	v_exp_f32_e32 v101, v101
	s_waitcnt lgkmcnt(10)
	v_mfma_f32_16x16x32_bf16 v[34:37], v[218:221], v[130:133], v[34:37]
	v_exp_f32_e32 v102, v102
	v_mfma_f32_16x16x32_bf16 v[38:41], v[218:221], v[134:137], v[38:41]
	v_exp_f32_e32 v103, v103
	s_waitcnt lgkmcnt(8)
	v_mfma_f32_16x16x32_bf16 v[42:45], v[222:225], v[130:133], v[42:45]
	v_exp_f32_e32 v104, v104
	v_mfma_f32_16x16x32_bf16 v[46:49], v[222:225], v[134:137], v[46:49]
	v_exp_f32_e32 v105, v105
	s_waitcnt lgkmcnt(6)
	v_mfma_f32_16x16x32_bf16 v[50:53], v[202:205], v[130:133], v[50:53]
	v_exp_f32_e32 v106, v106
	ds_read_b128 v[178:181], v234 offset:49152
	v_mfma_f32_16x16x32_bf16 v[54:57], v[202:205], v[134:137], v[54:57]
	v_exp_f32_e32 v107, v107
	s_waitcnt lgkmcnt(5)
	v_mfma_f32_16x16x32_bf16 v[58:61], v[206:209], v[130:133], v[58:61]
	v_exp_f32_e32 v108, v108
	ds_read_b128 v[182:185], v234 offset:53248
	v_mfma_f32_16x16x32_bf16 v[62:65], v[206:209], v[134:137], v[62:65]
	v_exp_f32_e32 v109, v109
	s_waitcnt lgkmcnt(4)
	v_mfma_f32_16x16x32_bf16 v[66:69], v[210:213], v[130:133], v[66:69]
	v_exp_f32_e32 v110, v110
	ds_read_b128 v[186:189], v234 offset:57344
	v_mfma_f32_16x16x32_bf16 v[70:73], v[210:213], v[134:137], v[70:73]
	v_exp_f32_e32 v111, v111
	s_waitcnt lgkmcnt(3)
	v_mfma_f32_16x16x32_bf16 v[74:77], v[214:217], v[130:133], v[74:77]
	v_exp_f32_e32 v112, v112
	ds_read_b128 v[190:193], v234 offset:61440
	v_mfma_f32_16x16x32_bf16 v[78:81], v[214:217], v[134:137], v[78:81]
	v_exp_f32_e32 v113, v113
	s_waitcnt vmcnt(0)
	s_barrier
	s_waitcnt lgkmcnt(3)
	v_mfma_f32_16x16x32_bf16 v[114:117], v[178:181], v[146:149], v[2:5]
	v_add_f32_e32 v250, v82, v250
	v_mfma_f32_16x16x32_bf16 v[118:121], v[178:181], v[162:165], v[2:5]
	ds_read_b128 v[178:181], v235 offset:49152
	v_add_f32_e32 v250, v83, v250
	v_add_f32_e32 v250, v84, v250
	s_waitcnt lgkmcnt(3)
	v_mfma_f32_16x16x32_bf16 v[122:125], v[182:185], v[146:149], v[2:5]
	v_add_f32_e32 v250, v85, v250
	v_mfma_f32_16x16x32_bf16 v[126:129], v[182:185], v[162:165], v[2:5]
	ds_read_b128 v[182:185], v235 offset:53248
	v_add_f32_e32 v250, v90, v250
	v_add_f32_e32 v250, v91, v250
	s_waitcnt lgkmcnt(3)
	v_mfma_f32_16x16x32_bf16 v[130:133], v[186:189], v[146:149], v[2:5]
	v_add_f32_e32 v250, v92, v250
	v_mfma_f32_16x16x32_bf16 v[134:137], v[186:189], v[162:165], v[2:5]
	ds_read_b128 v[186:189], v235 offset:57344
	v_add_f32_e32 v250, v93, v250
	v_cvt_pk_bf16_f32 v82, v82, v83
	s_waitcnt lgkmcnt(3)
	v_mfma_f32_16x16x32_bf16 v[138:141], v[190:193], v[146:149], v[2:5]
	v_cvt_pk_bf16_f32 v83, v84, v85
	v_mfma_f32_16x16x32_bf16 v[142:145], v[190:193], v[162:165], v[2:5]
	ds_read_b128 v[190:193], v235 offset:61440
	v_cvt_pk_bf16_f32 v84, v90, v91
	v_cvt_pk_bf16_f32 v85, v92, v93
	s_waitcnt lgkmcnt(3)
	v_mfma_f32_16x16x32_bf16 v[114:117], v[178:181], v[150:153], v[114:117]
	v_add_f32_e32 v251, v86, v251
	v_mfma_f32_16x16x32_bf16 v[118:121], v[178:181], v[166:169], v[118:121]
	ds_read_b128 v[178:181], v236 offset:49152
	v_add_f32_e32 v251, v87, v251
	v_add_f32_e32 v251, v88, v251
	s_waitcnt lgkmcnt(3)
	v_mfma_f32_16x16x32_bf16 v[122:125], v[182:185], v[150:153], v[122:125]
	v_add_f32_e32 v251, v89, v251
	v_mfma_f32_16x16x32_bf16 v[126:129], v[182:185], v[166:169], v[126:129]
	ds_read_b128 v[182:185], v236 offset:53248
	v_add_f32_e32 v251, v94, v251
	v_add_f32_e32 v251, v95, v251
	s_waitcnt lgkmcnt(3)
; #define SBAR() __builtin_amdgcn_sched_barrier(0)
; __device__ __forceinline__ void qkt(f32x16& p0, f32x16& p1, const bf16* Ks, const bf16x8* qr, int r32, int hi, const f32x16& negm) {
; #pragma unroll
;   for (int d0 = 0; d0 < 8; ++d0) { int cb = (d0 * 16 + hi * 8) * 2;
;     bf16x8 b0 = *reinterpret_cast<const bf16x8*>((const char*)Ks + KSWZ(r32, cb));
;     bf16x8 b1 = *reinterpret_cast<const bf16x8*>((const char*)Ks + KSWZ(32 + r32, cb));
;     if (d0 == 0) { p0 = __builtin_amdgcn_mfma_f32_32x32x16_bf16(b0, qr[0], negm, 0, 0, 0); p1 = __builtin_amdgcn_mfma_f32_32x32x16_bf16(b1, qr[0], negm, 0, 0, 0); }
;     else { p0 = __builtin_amdgcn_mfma_f32_32x32x16_bf16(b0, qr[d0], p0, 0, 0, 0); p1 = __builtin_amdgcn_mfma_f32_32x32x16_bf16(b1, qr[d0], p1, 0, 0, 0); } }
; }
; template <int D0> __device__ __forceinline__ void pv_one(f32x16& od, int vb, bf16x8 pa0, bf16x8 pa1, bf16x8 pa2, bf16x8 pa3) {
;   const s16x4 l0 = tr_read<v_rd_off(D0, 0, 0)>(vb), h0 = tr_read<v_rd_off(D0, 0, 1)>(vb), l1 = tr_read<v_rd_off(D0, 1, 0)>(vb), h1 = tr_read<v_rd_off(D0, 1, 1)>(vb);
;   const s16x4 l2 = tr_read<v_rd_off(D0, 2, 0)>(vb), h2 = tr_read<v_rd_off(D0, 2, 1)>(vb), l3 = tr_read<v_rd_off(D0, 3, 0)>(vb), h3 = tr_read<v_rd_off(D0, 3, 1)>(vb);
;   asm volatile("s_waitcnt lgkmcnt(0)" ::: "memory"); SBAR();
;     ...
;   od = __builtin_amdgcn_mfma_f32_32x32x16_bf16(pa0, PK(l0, h0), od, 0, 0, 0);
;   od = __builtin_amdgcn_mfma_f32_32x32x16_bf16(pa1, PK(l1, h1), od, 0, 0, 0);
;   od = __builtin_amdgcn_mfma_f32_32x32x16_bf16(pa2, PK(l2, h2), od, 0, 0, 0);
;   od = __builtin_amdgcn_mfma_f32_32x32x16_bf16(pa3, PK(l3, h3), od, 0, 0, 0);
;     ...
; }
; __device__ __forceinline__ void pv_d0(f32x16* o, int vb, bf16x8 pa0, bf16x8 pa1, bf16x8 pa2, bf16x8 pa3) {
;   pv_one<0>(o[0], vb, pa0, pa1, pa2, pa3); pv_one<1>(o[1], vb, pa0, pa1, pa2, pa3); pv_one<2>(o[2], vb, pa0, pa1, pa2, pa3); pv_one<3>(o[3], vb, pa0, pa1, pa2, pa3);
	v_mfma_f32_16x16x32_bf16 v[130:133], v[186:189], v[150:153], v[130:133]
	v_add_f32_e32 v251, v96, v251
	v_mfma_f32_16x16x32_bf16 v[134:137], v[186:189], v[166:169], v[134:137]
	ds_read_b128 v[186:189], v236 offset:57344
	v_add_f32_e32 v251, v97, v251
	v_cvt_pk_bf16_f32 v86, v86, v87
	s_waitcnt lgkmcnt(3)
	v_mfma_f32_16x16x32_bf16 v[138:141], v[190:193], v[150:153], v[138:141]
	v_cvt_pk_bf16_f32 v87, v88, v89
	v_mfma_f32_16x16x32_bf16 v[142:145], v[190:193], v[166:169], v[142:145]
	ds_read_b128 v[190:193], v236 offset:61440
	v_cvt_pk_bf16_f32 v88, v94, v95
	v_cvt_pk_bf16_f32 v89, v96, v97
	s_waitcnt lgkmcnt(3)
	v_mfma_f32_16x16x32_bf16 v[114:117], v[178:181], v[154:157], v[114:117]
	v_add_f32_e32 v250, v98, v250
	v_mfma_f32_16x16x32_bf16 v[118:121], v[178:181], v[170:173], v[118:121]
	ds_read_b128 v[178:181], v237 offset:49152
	v_add_f32_e32 v250, v99, v250
	v_add_f32_e32 v250, v100, v250
	s_waitcnt lgkmcnt(3)
	v_mfma_f32_16x16x32_bf16 v[122:125], v[182:185], v[154:157], v[122:125]
	v_add_f32_e32 v250, v101, v250
	v_mfma_f32_16x16x32_bf16 v[126:129], v[182:185], v[170:173], v[126:129]
	ds_read_b128 v[182:185], v237 offset:53248
	v_add_f32_e32 v250, v106, v250
	v_add_f32_e32 v250, v107, v250
	s_waitcnt lgkmcnt(3)
	v_mfma_f32_16x16x32_bf16 v[130:133], v[186:189], v[154:157], v[130:133]
	v_add_f32_e32 v250, v108, v250
	ds_read_b64_tr_b16 v[202:203], v238 offset:32768
	ds_read_b64_tr_b16 v[204:205], v238 offset:36864
	v_mfma_f32_16x16x32_bf16 v[134:137], v[186:189], v[170:173], v[134:137]
	ds_read_b128 v[186:189], v237 offset:57344
	v_add_f32_e32 v250, v109, v250
	v_cvt_pk_bf16_f32 v98, v98, v99
	s_waitcnt lgkmcnt(5)
	v_mfma_f32_16x16x32_bf16 v[138:141], v[190:193], v[154:157], v[138:141]
	v_cvt_pk_bf16_f32 v99, v100, v101
	ds_read_b64_tr_b16 v[206:207], v239 offset:32768
	ds_read_b64_tr_b16 v[208:209], v239 offset:36864
	v_mfma_f32_16x16x32_bf16 v[142:145], v[190:193], v[170:173], v[142:145]
	ds_read_b128 v[190:193], v237 offset:61440
	v_cvt_pk_bf16_f32 v100, v106, v107
	v_cvt_pk_bf16_f32 v101, v108, v109
	s_waitcnt lgkmcnt(7)
	v_mfma_f32_16x16x32_bf16 v[114:117], v[178:181], v[158:161], v[114:117]
	v_add_f32_e32 v251, v102, v251
	ds_read_b64_tr_b16 v[210:211], v240 offset:32768
	ds_read_b64_tr_b16 v[212:213], v240 offset:36864
	v_mfma_f32_16x16x32_bf16 v[118:121], v[178:181], v[174:177], v[118:121]
	v_add_f32_e32 v251, v103, v251
	v_add_f32_e32 v251, v104, v251
	s_waitcnt lgkmcnt(8)
	v_mfma_f32_16x16x32_bf16 v[122:125], v[182:185], v[158:161], v[122:125]
	v_add_f32_e32 v251, v105, v251
	ds_read_b64_tr_b16 v[214:215], v241 offset:32768
	ds_read_b64_tr_b16 v[216:217], v241 offset:36864
	v_mfma_f32_16x16x32_bf16 v[126:129], v[182:185], v[174:177], v[126:129]
	v_add_f32_e32 v251, v110, v251
	v_add_f32_e32 v251, v111, v251
	s_waitcnt lgkmcnt(7)
	v_mfma_f32_16x16x32_bf16 v[130:133], v[186:189], v[158:161], v[130:133]
	v_add_f32_e32 v251, v112, v251
	ds_read_b64_tr_b16 v[218:219], v242 offset:32768
	ds_read_b64_tr_b16 v[220:221], v242 offset:36864
	v_mfma_f32_16x16x32_bf16 v[134:137], v[186:189], v[174:177], v[134:137]
	v_add_f32_e32 v251, v113, v251
	v_cvt_pk_bf16_f32 v102, v102, v103
	s_waitcnt lgkmcnt(6)
	v_mfma_f32_16x16x32_bf16 v[138:141], v[190:193], v[158:161], v[138:141]
	v_cvt_pk_bf16_f32 v103, v104, v105
	ds_read_b64_tr_b16 v[222:223], v243 offset:32768
	ds_read_b64_tr_b16 v[224:225], v243 offset:36864
	v_mfma_f32_16x16x32_bf16 v[142:145], v[190:193], v[174:177], v[142:145]
	v_cvt_pk_bf16_f32 v104, v110, v111
	v_cvt_pk_bf16_f32 v105, v112, v113
	v_mfma_f32_16x16x32_bf16 v[18:21], v[202:205], v[82:85], v[18:21]
	v_exp_f32_e32 v114, v114
	v_mfma_f32_16x16x32_bf16 v[22:25], v[202:205], v[86:89], v[22:25]
	ds_read_b64_tr_b16 v[202:203], v244 offset:32768
	ds_read_b64_tr_b16 v[204:205], v244 offset:36864
	v_exp_f32_e32 v115, v115
	v_mfma_f32_16x16x32_bf16 v[26:29], v[206:209], v[82:85], v[26:29]
	v_exp_f32_e32 v116, v116
	v_mfma_f32_16x16x32_bf16 v[30:33], v[206:209], v[86:89], v[30:33]
	ds_read_b64_tr_b16 v[206:207], v245 offset:32768
	ds_read_b64_tr_b16 v[208:209], v245 offset:36864
	v_exp_f32_e32 v117, v117
	s_waitcnt lgkmcnt(10)
	v_mfma_f32_16x16x32_bf16 v[34:37], v[210:213], v[82:85], v[34:37]
	v_exp_f32_e32 v118, v118
	v_mfma_f32_16x16x32_bf16 v[38:41], v[210:213], v[86:89], v[38:41]
	ds_read_b64_tr_b16 v[210:211], v238 offset:40960
	ds_read_b64_tr_b16 v[212:213], v238 offset:45056
	v_exp_f32_e32 v119, v119
	s_waitcnt lgkmcnt(10)
	v_mfma_f32_16x16x32_bf16 v[42:45], v[214:217], v[82:85], v[42:45]
	v_exp_f32_e32 v120, v120
	v_mfma_f32_16x16x32_bf16 v[46:49], v[214:217], v[86:89], v[46:49]
	ds_read_b64_tr_b16 v[214:215], v239 offset:40960
	ds_read_b64_tr_b16 v[216:217], v239 offset:45056
	v_exp_f32_e32 v121, v121
	s_waitcnt lgkmcnt(10)
	v_mfma_f32_16x16x32_bf16 v[50:53], v[218:221], v[82:85], v[50:53]
	v_exp_f32_e32 v122, v122
	v_mfma_f32_16x16x32_bf16 v[54:57], v[218:221], v[86:89], v[54:57]
	ds_read_b64_tr_b16 v[218:219], v240 offset:40960
	ds_read_b64_tr_b16 v[220:221], v240 offset:45056
	v_exp_f32_e32 v123, v123
	s_waitcnt lgkmcnt(10)
	v_mfma_f32_16x16x32_bf16 v[58:61], v[222:225], v[82:85], v[58:61]
	v_exp_f32_e32 v124, v124
	v_mfma_f32_16x16x32_bf16 v[62:65], v[222:225], v[86:89], v[62:65]
	ds_read_b64_tr_b16 v[222:223], v241 offset:40960
	ds_read_b64_tr_b16 v[224:225], v241 offset:45056
	v_exp_f32_e32 v125, v125
	s_waitcnt lgkmcnt(10)
	v_mfma_f32_16x16x32_bf16 v[66:69], v[202:205], v[82:85], v[66:69]
	v_exp_f32_e32 v126, v126
	v_mfma_f32_16x16x32_bf16 v[70:73], v[202:205], v[86:89], v[70:73]
	ds_read_b64_tr_b16 v[202:203], v242 offset:40960
	ds_read_b64_tr_b16 v[204:205], v242 offset:45056
	v_exp_f32_e32 v127, v127
	s_waitcnt lgkmcnt(10)
; __device__ __forceinline__ void partialSM(f32x16& p0, f32x16& p1, float mC) {
;   (void)mC; (void)p1;
;   for (int r = 0; r < 16; ++r) p0[r] = __builtin_amdgcn_exp2f(p0[r]);
; }
; __device__ __forceinline__ void finishSM(f32x16& p0, f32x16& p1, float& l_reg, bf16x8& pa0, bf16x8& pa1, bf16x8& pa2, bf16x8& pa3) {
;   for (int r = 0; r < 16; ++r) p1[r] = __builtin_amdgcn_exp2f(p1[r]);
;   float ps = 0; for (int r = 0; r < 16; ++r) ps += p0[r]; for (int r = 0; r < 16; ++r) ps += p1[r];
;   { auto rr = __builtin_amdgcn_permlane32_swap(__float_as_uint(ps), __float_as_uint(ps), false, false);
;     ps = __uint_as_float(rr[0]) + __uint_as_float(rr[1]); }
;   l_reg += ps;
;     ...
;   PK4(p0, 0, pa0); PK4(p0, 8, pa1); PK4(p1, 0, pa2); PK4(p1, 8, pa3);
;     ...
; }
; __device__ __forceinline__ void qkt(f32x16& p0, f32x16& p1, const bf16* Ks, const bf16x8* qr, int r32, int hi, const f32x16& negm) {
; #pragma unroll
;   for (int d0 = 0; d0 < 8; ++d0) { int cb = (d0 * 16 + hi * 8) * 2;
;     bf16x8 b0 = *reinterpret_cast<const bf16x8*>((const char*)Ks + KSWZ(r32, cb));
;     bf16x8 b1 = *reinterpret_cast<const bf16x8*>((const char*)Ks + KSWZ(32 + r32, cb));
;     if (d0 == 0) { p0 = __builtin_amdgcn_mfma_f32_32x32x16_bf16(b0, qr[0], negm, 0, 0, 0); p1 = __builtin_amdgcn_mfma_f32_32x32x16_bf16(b1, qr[0], negm, 0, 0, 0); }
;     else { p0 = __builtin_amdgcn_mfma_f32_32x32x16_bf16(b0, qr[d0], p0, 0, 0, 0); p1 = __builtin_amdgcn_mfma_f32_32x32x16_bf16(b1, qr[d0], p1, 0, 0, 0); } }
; }
; __device__ __forceinline__ int v_st(int k, int c) { const int kk = (k & ~0xC) | ((k & 4) << 1) | ((k & 8) >> 1); return ((kk >> 3) * 4 + (c >> 5)) * 512 + ((kk & 7) * 32 + (c & 31)) * 2; }
; __device__ __forceinline__ int v_rd_base(int lane) { return ((lane & 3) << 3) | (((lane >> 2) & 3) << 6) | (((lane >> 4) & 1) << 5) | (((lane >> 5) & 1) << 8); }
; template <int OFF> __device__ __forceinline__ s16x4 tr_read(int vb) {
;   s16x4 r; asm volatile("ds_read_b64_tr_b16 %0, %1 offset:%2" : "=&v"(r) : "v"(vb), "i"(OFF) : "memory"); return r;
; }
; template <int D0> __device__ __forceinline__ void pv_one(f32x16& od, int vb, bf16x8 pa0, bf16x8 pa1, bf16x8 pa2, bf16x8 pa3) {
;   const s16x4 l0 = tr_read<v_rd_off(D0, 0, 0)>(vb), h0 = tr_read<v_rd_off(D0, 0, 1)>(vb), l1 = tr_read<v_rd_off(D0, 1, 0)>(vb), h1 = tr_read<v_rd_off(D0, 1, 1)>(vb);
	v_mfma_f32_16x16x32_bf16 v[74:77], v[206:209], v[82:85], v[74:77]
	v_exp_f32_e32 v128, v128
	v_mfma_f32_16x16x32_bf16 v[78:81], v[206:209], v[86:89], v[78:81]
	ds_read_b64_tr_b16 v[206:207], v243 offset:40960
	ds_read_b64_tr_b16 v[208:209], v243 offset:45056
	v_exp_f32_e32 v129, v129
	s_waitcnt lgkmcnt(10)
	v_mfma_f32_16x16x32_bf16 v[18:21], v[210:213], v[98:101], v[18:21]
	v_exp_f32_e32 v130, v130
	v_mfma_f32_16x16x32_bf16 v[22:25], v[210:213], v[102:105], v[22:25]
	ds_read_b64_tr_b16 v[210:211], v244 offset:40960
	ds_read_b64_tr_b16 v[212:213], v244 offset:45056
	v_exp_f32_e32 v131, v131
	s_waitcnt lgkmcnt(10)
	v_mfma_f32_16x16x32_bf16 v[26:29], v[214:217], v[98:101], v[26:29]
	v_exp_f32_e32 v132, v132
	v_mfma_f32_16x16x32_bf16 v[30:33], v[214:217], v[102:105], v[30:33]
	ds_read_b64_tr_b16 v[214:215], v245 offset:40960
	ds_read_b64_tr_b16 v[216:217], v245 offset:45056
	v_exp_f32_e32 v133, v133
	s_waitcnt lgkmcnt(10)
	v_mfma_f32_16x16x32_bf16 v[34:37], v[218:221], v[98:101], v[34:37]
	v_exp_f32_e32 v134, v134
	v_mfma_f32_16x16x32_bf16 v[38:41], v[218:221], v[102:105], v[38:41]
	v_exp_f32_e32 v135, v135
	s_waitcnt lgkmcnt(8)
	v_mfma_f32_16x16x32_bf16 v[42:45], v[222:225], v[98:101], v[42:45]
	v_exp_f32_e32 v136, v136
	v_mfma_f32_16x16x32_bf16 v[46:49], v[222:225], v[102:105], v[46:49]
	v_exp_f32_e32 v137, v137
	s_waitcnt lgkmcnt(6)
	v_mfma_f32_16x16x32_bf16 v[50:53], v[202:205], v[98:101], v[50:53]
	v_exp_f32_e32 v138, v138
	v_mfma_f32_16x16x32_bf16 v[54:57], v[202:205], v[102:105], v[54:57]
	v_exp_f32_e32 v139, v139
	s_waitcnt lgkmcnt(4)
	v_mfma_f32_16x16x32_bf16 v[58:61], v[206:209], v[98:101], v[58:61]
	v_exp_f32_e32 v140, v140
	v_mfma_f32_16x16x32_bf16 v[62:65], v[206:209], v[102:105], v[62:65]
	v_exp_f32_e32 v141, v141
	s_waitcnt lgkmcnt(2)
	v_mfma_f32_16x16x32_bf16 v[66:69], v[210:213], v[98:101], v[66:69]
	v_exp_f32_e32 v142, v142
	v_mfma_f32_16x16x32_bf16 v[70:73], v[210:213], v[102:105], v[70:73]
	v_exp_f32_e32 v143, v143
	s_waitcnt lgkmcnt(0)
	v_mfma_f32_16x16x32_bf16 v[74:77], v[214:217], v[98:101], v[74:77]
	v_exp_f32_e32 v144, v144
	v_mfma_f32_16x16x32_bf16 v[78:81], v[214:217], v[102:105], v[78:81]
	v_exp_f32_e32 v145, v145
	s_waitcnt vmcnt(0)
	v_add_f32_e32 v250, v114, v250
	v_add_f32_e32 v250, v115, v250
	v_add_f32_e32 v250, v116, v250
	v_add_f32_e32 v250, v117, v250
	v_add_f32_e32 v250, v122, v250
	v_add_f32_e32 v250, v123, v250
	v_add_f32_e32 v250, v124, v250
	v_add_f32_e32 v250, v125, v250
	v_cvt_pk_bf16_f32 v114, v114, v115
	v_cvt_pk_bf16_f32 v115, v116, v117
	v_cvt_pk_bf16_f32 v116, v122, v123
	v_cvt_pk_bf16_f32 v117, v124, v125
	v_add_f32_e32 v251, v118, v251
	v_add_f32_e32 v251, v119, v251
	v_add_f32_e32 v251, v120, v251
	v_add_f32_e32 v251, v121, v251
	v_add_f32_e32 v251, v126, v251
	v_add_f32_e32 v251, v127, v251
	v_add_f32_e32 v251, v128, v251
	v_add_f32_e32 v251, v129, v251
	v_cvt_pk_bf16_f32 v118, v118, v119
	v_cvt_pk_bf16_f32 v119, v120, v121
	v_cvt_pk_bf16_f32 v120, v126, v127
	v_cvt_pk_bf16_f32 v121, v128, v129
	v_add_f32_e32 v250, v130, v250
	v_add_f32_e32 v250, v131, v250
	v_add_f32_e32 v250, v132, v250
	v_add_f32_e32 v250, v133, v250
	v_add_f32_e32 v250, v138, v250
	v_add_f32_e32 v250, v139, v250
	v_add_f32_e32 v250, v140, v250
	v_add_f32_e32 v250, v141, v250
	v_cvt_pk_bf16_f32 v130, v130, v131
	v_cvt_pk_bf16_f32 v131, v132, v133
	v_cvt_pk_bf16_f32 v132, v138, v139
	v_cvt_pk_bf16_f32 v133, v140, v141
	v_add_f32_e32 v251, v134, v251
	v_add_f32_e32 v251, v135, v251
	v_add_f32_e32 v251, v136, v251
	v_add_f32_e32 v251, v137, v251
	v_add_f32_e32 v251, v142, v251
	v_add_f32_e32 v251, v143, v251
	v_add_f32_e32 v251, v144, v251
	v_add_f32_e32 v251, v145, v251
	v_cvt_pk_bf16_f32 v134, v134, v135
	v_cvt_pk_bf16_f32 v135, v136, v137
	v_cvt_pk_bf16_f32 v136, v142, v143
	v_cvt_pk_bf16_f32 v137, v144, v145
	ds_read_b64_tr_b16 v[202:203], v238 offset:49152
	ds_read_b64_tr_b16 v[204:205], v238 offset:53248
	ds_read_b64_tr_b16 v[206:207], v239 offset:49152
	ds_read_b64_tr_b16 v[208:209], v239 offset:53248
	ds_read_b64_tr_b16 v[210:211], v240 offset:49152
	ds_read_b64_tr_b16 v[212:213], v240 offset:53248
	ds_read_b64_tr_b16 v[214:215], v241 offset:49152
	ds_read_b64_tr_b16 v[216:217], v241 offset:53248
	ds_read_b64_tr_b16 v[218:219], v242 offset:49152
	ds_read_b64_tr_b16 v[220:221], v242 offset:53248
	ds_read_b64_tr_b16 v[222:223], v243 offset:49152
	ds_read_b64_tr_b16 v[224:225], v243 offset:53248
	s_waitcnt lgkmcnt(10)
	v_mfma_f32_16x16x32_bf16 v[18:21], v[202:205], v[114:117], v[18:21]
	v_mfma_f32_16x16x32_bf16 v[22:25], v[202:205], v[118:121], v[22:25]
	ds_read_b64_tr_b16 v[202:203], v244 offset:49152
	ds_read_b64_tr_b16 v[204:205], v244 offset:53248
	s_waitcnt lgkmcnt(10)
	v_mfma_f32_16x16x32_bf16 v[26:29], v[206:209], v[114:117], v[26:29]
	v_mfma_f32_16x16x32_bf16 v[30:33], v[206:209], v[118:121], v[30:33]
	ds_read_b64_tr_b16 v[206:207], v245 offset:49152
	ds_read_b64_tr_b16 v[208:209], v245 offset:53248
	s_waitcnt lgkmcnt(10)
	v_mfma_f32_16x16x32_bf16 v[34:37], v[210:213], v[114:117], v[34:37]
	v_mfma_f32_16x16x32_bf16 v[38:41], v[210:213], v[118:121], v[38:41]
	ds_read_b64_tr_b16 v[210:211], v238 offset:57344
	ds_read_b64_tr_b16 v[212:213], v238 offset:61440
	s_waitcnt lgkmcnt(10)
	v_mfma_f32_16x16x32_bf16 v[42:45], v[214:217], v[114:117], v[42:45]
	v_mfma_f32_16x16x32_bf16 v[46:49], v[214:217], v[118:121], v[46:49]
	ds_read_b64_tr_b16 v[214:215], v239 offset:57344
	ds_read_b64_tr_b16 v[216:217], v239 offset:61440
	s_waitcnt lgkmcnt(10)
	v_mfma_f32_16x16x32_bf16 v[50:53], v[218:221], v[114:117], v[50:53]
	v_mfma_f32_16x16x32_bf16 v[54:57], v[218:221], v[118:121], v[54:57]
	ds_read_b64_tr_b16 v[218:219], v240 offset:57344
	ds_read_b64_tr_b16 v[220:221], v240 offset:61440
	s_waitcnt lgkmcnt(10)
; #define SBAR() __builtin_amdgcn_sched_barrier(0)
; __device__ __forceinline__ int crow(int r, int hi) { return (r & 3) + 8 * (r >> 2) + 4 * hi; }
; template <typename TQ> ...
;     ...
;   SBAR(); qkt(pB0, pB1, (bf16*)((char*)K_lds + SHM_K), qr, r32, hi, negm);
;   finishSM(pA0, pA1, l_reg, pa0, pa1, pa2, pa3); SBAR();
;   pv_d0(o, vb0, pa0, pa1, pa2, pa3); partialSM(pB0, pB1, mC);
;   __syncthreads();
;   finishSM(pB0, pB1, l_reg, pa0, pa1, pa2, pa3); SBAR();
;   pv_d0(o, vb0 + (int)SHM_V, pa0, pa1, pa2, pa3);
;   if (hi == 0) li_l[r32] = l_reg; asm volatile("s_waitcnt lgkmcnt(0)" ::: "memory");
;   float rli[16];
; #pragma unroll
;   for (int r = 0; r < 16; ++r) rli[r] = __builtin_amdgcn_rcpf(li_l[crow(r, hi)]);
;   int le = (int)(threadIdx.x & 63u); asm volatile("" : "+v"(le));
;   const int r32e = le & 31, hie = le >> 5;
;   bf16* Ow = Ob + (long)(wid * QBLK) * LDO;
; #pragma unroll
;   for (int r = 0; r < 16; ++r) { int orow = crow(r, hie);
;     for (int d0 = 0; d0 < 4; ++d0) Ow[(long)orow * LDO + d0 * 32 + r32e] = __float2bfloat16(o[d0][r] * rli[r]); }
; __global__ void __launch_bounds__(NTHR, 2) fwd_megakernel(KArgs a) {
;     ...
;         for (int i = 0; i < upb; ++i) {
;             const int unit = vcu * upb + i; if (unit >= 512) break;
;             const int grp = unit >> 7, rem = unit & 127, gq = rem >> 5, qb = rem & 31, b = grp >> 1, kvh = grp & 1, h = kvh * 4 + gq;
;             const size_t qoff = ((size_t)(b * SEQ + qb * 256)) * DM + h * 128, koff = (size_t)b * SKV * 256 + kvh * 128;
;             att::attn_dense_body<att::bf16>(Q + qoff, Kb + koff, Vb + koff, O + qoff, SKV, (char*)lds_raw, mC, a.g_q, (const float*)(ws + WS_ROPE), (const float*)(ws + WS_ROPE) + 4096, qb * 256);
;             __syncthreads();
;         }
	v_mfma_f32_16x16x32_bf16 v[58:61], v[222:225], v[114:117], v[58:61]
	v_mfma_f32_16x16x32_bf16 v[62:65], v[222:225], v[118:121], v[62:65]
	ds_read_b64_tr_b16 v[222:223], v241 offset:57344
	ds_read_b64_tr_b16 v[224:225], v241 offset:61440
	s_waitcnt lgkmcnt(10)
	v_mfma_f32_16x16x32_bf16 v[66:69], v[202:205], v[114:117], v[66:69]
	v_mfma_f32_16x16x32_bf16 v[70:73], v[202:205], v[118:121], v[70:73]
	ds_read_b64_tr_b16 v[202:203], v242 offset:57344
	ds_read_b64_tr_b16 v[204:205], v242 offset:61440
	s_waitcnt lgkmcnt(10)
	v_mfma_f32_16x16x32_bf16 v[74:77], v[206:209], v[114:117], v[74:77]
	v_mfma_f32_16x16x32_bf16 v[78:81], v[206:209], v[118:121], v[78:81]
	ds_read_b64_tr_b16 v[206:207], v243 offset:57344
	ds_read_b64_tr_b16 v[208:209], v243 offset:61440
	s_waitcnt lgkmcnt(10)
	v_mfma_f32_16x16x32_bf16 v[18:21], v[210:213], v[130:133], v[18:21]
	v_mfma_f32_16x16x32_bf16 v[22:25], v[210:213], v[134:137], v[22:25]
	ds_read_b64_tr_b16 v[210:211], v244 offset:57344
	ds_read_b64_tr_b16 v[212:213], v244 offset:61440
	s_waitcnt lgkmcnt(10)
	v_mfma_f32_16x16x32_bf16 v[26:29], v[214:217], v[130:133], v[26:29]
	v_mfma_f32_16x16x32_bf16 v[30:33], v[214:217], v[134:137], v[30:33]
	ds_read_b64_tr_b16 v[214:215], v245 offset:57344
	ds_read_b64_tr_b16 v[216:217], v245 offset:61440
	s_waitcnt lgkmcnt(10)
	v_mfma_f32_16x16x32_bf16 v[34:37], v[218:221], v[130:133], v[34:37]
	v_mfma_f32_16x16x32_bf16 v[38:41], v[218:221], v[134:137], v[38:41]
	s_waitcnt lgkmcnt(8)
	v_mfma_f32_16x16x32_bf16 v[42:45], v[222:225], v[130:133], v[42:45]
	v_mfma_f32_16x16x32_bf16 v[46:49], v[222:225], v[134:137], v[46:49]
	s_waitcnt lgkmcnt(6)
	v_mfma_f32_16x16x32_bf16 v[50:53], v[202:205], v[130:133], v[50:53]
	v_mfma_f32_16x16x32_bf16 v[54:57], v[202:205], v[134:137], v[54:57]
	s_waitcnt lgkmcnt(4)
	v_mfma_f32_16x16x32_bf16 v[58:61], v[206:209], v[130:133], v[58:61]
	v_mfma_f32_16x16x32_bf16 v[62:65], v[206:209], v[134:137], v[62:65]
	s_waitcnt lgkmcnt(2)
	v_mfma_f32_16x16x32_bf16 v[66:69], v[210:213], v[130:133], v[66:69]
	v_mfma_f32_16x16x32_bf16 v[70:73], v[210:213], v[134:137], v[70:73]
	s_waitcnt lgkmcnt(0)
	v_mfma_f32_16x16x32_bf16 v[74:77], v[214:217], v[130:133], v[74:77]
	v_mfma_f32_16x16x32_bf16 v[78:81], v[214:217], v[134:137], v[78:81]
	s_setprio 0
	ds_swizzle_b32 v6, v250 offset:swizzle(SWAP,16)
	s_waitcnt lgkmcnt(0)
	v_add_f32_e32 v250, v250, v6
	v_mov_b32_e32 v6, v250
	s_nop 1
	v_permlane32_swap_b32_e32 v250, v6
	v_add_f32_e32 v250, v250, v6
	v_rcp_f32_e32 v250, v250
	ds_swizzle_b32 v6, v251 offset:swizzle(SWAP,16)
	s_waitcnt lgkmcnt(0)
	v_add_f32_e32 v251, v251, v6
	v_mov_b32_e32 v6, v251
	s_nop 1
	v_permlane32_swap_b32_e32 v251, v6
	v_add_f32_e32 v251, v251, v6
	v_rcp_f32_e32 v251, v251
	s_add_u32 s12, s71, s48
	s_addc_u32 s13, s72, s49
	v_add_u32_e32 v201, s52, v16
	v_lshlrev_b32_e32 v201, 11, v201
	v_lshl_or_b32 v7, v17, 3, v201
	v_add_u32_e32 v200, 0x8000, v7
	v_mul_f32_e32 v18, v18, v250
	v_mul_f32_e32 v19, v19, v250
	v_mul_f32_e32 v20, v20, v250
	v_mul_f32_e32 v21, v21, v250
	v_cvt_pk_bf16_f32 v18, v18, v19
	v_cvt_pk_bf16_f32 v19, v20, v21
	global_store_dwordx2 v7, v[18:19], s[12:13] offset:0
	v_mul_f32_e32 v22, v22, v251
	v_mul_f32_e32 v23, v23, v251
	v_mul_f32_e32 v24, v24, v251
	v_mul_f32_e32 v25, v25, v251
	v_cvt_pk_bf16_f32 v22, v22, v23
	v_cvt_pk_bf16_f32 v23, v24, v25
	global_store_dwordx2 v200, v[22:23], s[12:13] offset:0
	v_mul_f32_e32 v26, v26, v250
	v_mul_f32_e32 v27, v27, v250
	v_mul_f32_e32 v28, v28, v250
	v_mul_f32_e32 v29, v29, v250
	v_cvt_pk_bf16_f32 v26, v26, v27
	v_cvt_pk_bf16_f32 v27, v28, v29
	global_store_dwordx2 v7, v[26:27], s[12:13] offset:32
	v_mul_f32_e32 v30, v30, v251
	v_mul_f32_e32 v31, v31, v251
	v_mul_f32_e32 v32, v32, v251
	v_mul_f32_e32 v33, v33, v251
	v_cvt_pk_bf16_f32 v30, v30, v31
	v_cvt_pk_bf16_f32 v31, v32, v33
	global_store_dwordx2 v200, v[30:31], s[12:13] offset:32
	v_mul_f32_e32 v34, v34, v250
	v_mul_f32_e32 v35, v35, v250
	v_mul_f32_e32 v36, v36, v250
	v_mul_f32_e32 v37, v37, v250
	v_cvt_pk_bf16_f32 v34, v34, v35
	v_cvt_pk_bf16_f32 v35, v36, v37
	global_store_dwordx2 v7, v[34:35], s[12:13] offset:64
	v_mul_f32_e32 v38, v38, v251
	v_mul_f32_e32 v39, v39, v251
	v_mul_f32_e32 v40, v40, v251
	v_mul_f32_e32 v41, v41, v251
	v_cvt_pk_bf16_f32 v38, v38, v39
	v_cvt_pk_bf16_f32 v39, v40, v41
	global_store_dwordx2 v200, v[38:39], s[12:13] offset:64
	v_mul_f32_e32 v42, v42, v250
	v_mul_f32_e32 v43, v43, v250
	v_mul_f32_e32 v44, v44, v250
	v_mul_f32_e32 v45, v45, v250
	v_cvt_pk_bf16_f32 v42, v42, v43
	v_cvt_pk_bf16_f32 v43, v44, v45
	global_store_dwordx2 v7, v[42:43], s[12:13] offset:96
	v_mul_f32_e32 v46, v46, v251
	v_mul_f32_e32 v47, v47, v251
	v_mul_f32_e32 v48, v48, v251
	v_mul_f32_e32 v49, v49, v251
	v_cvt_pk_bf16_f32 v46, v46, v47
	v_cvt_pk_bf16_f32 v47, v48, v49
	global_store_dwordx2 v200, v[46:47], s[12:13] offset:96
	v_mul_f32_e32 v50, v50, v250
	v_mul_f32_e32 v51, v51, v250
	v_mul_f32_e32 v52, v52, v250
	v_mul_f32_e32 v53, v53, v250
	v_cvt_pk_bf16_f32 v50, v50, v51
	v_cvt_pk_bf16_f32 v51, v52, v53
	global_store_dwordx2 v7, v[50:51], s[12:13] offset:128
	v_mul_f32_e32 v54, v54, v251
	v_mul_f32_e32 v55, v55, v251
	v_mul_f32_e32 v56, v56, v251
	v_mul_f32_e32 v57, v57, v251
	v_cvt_pk_bf16_f32 v54, v54, v55
	v_cvt_pk_bf16_f32 v55, v56, v57
	global_store_dwordx2 v200, v[54:55], s[12:13] offset:128
	v_mul_f32_e32 v58, v58, v250
	v_mul_f32_e32 v59, v59, v250
	v_mul_f32_e32 v60, v60, v250
	v_mul_f32_e32 v61, v61, v250
	v_cvt_pk_bf16_f32 v58, v58, v59
	v_cvt_pk_bf16_f32 v59, v60, v61
	global_store_dwordx2 v7, v[58:59], s[12:13] offset:160
	v_mul_f32_e32 v62, v62, v251
	v_mul_f32_e32 v63, v63, v251
	v_mul_f32_e32 v64, v64, v251
	v_mul_f32_e32 v65, v65, v251
	v_cvt_pk_bf16_f32 v62, v62, v63
	v_cvt_pk_bf16_f32 v63, v64, v65
	global_store_dwordx2 v200, v[62:63], s[12:13] offset:160
	v_mul_f32_e32 v66, v66, v250
	v_mul_f32_e32 v67, v67, v250
	v_mul_f32_e32 v68, v68, v250
	v_mul_f32_e32 v69, v69, v250
	v_cvt_pk_bf16_f32 v66, v66, v67
	v_cvt_pk_bf16_f32 v67, v68, v69
	global_store_dwordx2 v7, v[66:67], s[12:13] offset:192
	v_mul_f32_e32 v70, v70, v251
	v_mul_f32_e32 v71, v71, v251
	v_mul_f32_e32 v72, v72, v251
	v_mul_f32_e32 v73, v73, v251
	v_cvt_pk_bf16_f32 v70, v70, v71
	v_cvt_pk_bf16_f32 v71, v72, v73
	global_store_dwordx2 v200, v[70:71], s[12:13] offset:192
	v_mul_f32_e32 v74, v74, v250
	v_mul_f32_e32 v75, v75, v250
	v_mul_f32_e32 v76, v76, v250
	v_mul_f32_e32 v77, v77, v250
	v_cvt_pk_bf16_f32 v74, v74, v75
	v_cvt_pk_bf16_f32 v75, v76, v77
	global_store_dwordx2 v7, v[74:75], s[12:13] offset:224
	v_mul_f32_e32 v78, v78, v251
	v_mul_f32_e32 v79, v79, v251
	v_mul_f32_e32 v80, v80, v251
	v_mul_f32_e32 v81, v81, v251
	v_cvt_pk_bf16_f32 v78, v78, v79
	v_cvt_pk_bf16_f32 v79, v80, v81
	global_store_dwordx2 v200, v[78:79], s[12:13] offset:224
	s_add_i32 s74, s74, 1
	s_add_i32 s94, s94, 1
	s_cmp_eq_u32 s74, s66
	s_cselect_b64 s[0:1], -1, 0
	s_barrier
	s_branch .LBB0_818
